# v75 + diff-attention loops: per-step lane-pair exchange of the row sum removed, partial sums exchanged once per unit
# speedup vs baseline: 1.0024x; 1.0024x over previous
.LBB0_898:
	v_mov_b32_e32 v216, 0
	s_add_i32 s0, s26, 0xfffff800
	s_cmpk_lt_i32 s26, 0x800
	s_cselect_b64 s[16:17], -1, 0
	s_and_b64 vcc, s[16:17], exec
	s_cselect_b32 s0, s26, s0
	s_cselect_b32 s1, 10, 4
	s_ashr_i32 s0, s0, s1
	s_mov_b64 s[18:19], -1
	s_cbranch_vccnz .LBB0_900
	s_lshl_b32 s4, s0, 8
	s_ashr_i32 s5, s4, 31
	s_add_u32 s14, s4, 0x8000
	s_addc_u32 s15, s5, 0
	s_ashr_i32 s1, s0, 31
	s_mov_b64 s[18:19], 0

.LBB0_906:
	v_lshl_add_u64 v[66:67], v[178:179], 0, s[12:13]
	s_mov_b32 m0, s35
	global_load_lds_dwordx4 v[66:67], off
	v_lshl_add_u64 v[66:67], v[176:177], 0, s[12:13]
	s_mov_b32 m0, s86
	global_load_lds_dwordx4 v[66:67], off
	ds_read_b128 v[66:69], v188 offset:40960
	ds_read_b128 v[70:73], v188 offset:45056
	ds_read_b128 v[82:85], v189 offset:40960
	ds_read_b128 v[86:89], v189 offset:45056
	ds_read_b128 v[90:93], v190 offset:40960
	ds_read_b128 v[176:179], v190 offset:45056
	ds_read_b128 v[192:195], v191 offset:40960
	ds_read_b128 v[196:199], v191 offset:45056
	v_add_f32_e32 v216, v216, v1
	s_waitcnt lgkmcnt(0)
	v_mfma_f32_32x32x16_bf16 v[112:127], v[66:69], v[128:131], 0
	v_mfma_f32_32x32x16_bf16 v[66:81], v[70:73], v[128:131], 0
	v_mfma_f32_32x32x16_bf16 v[66:81], v[86:89], v[132:135], v[66:81]
	v_mfma_f32_32x32x16_bf16 v[112:127], v[82:85], v[132:135], v[112:127]
	v_add_f32_e32 v86, v238, v239
	v_add_f32_e32 v87, v222, v223
	v_mfma_f32_32x32x16_bf16 v[66:81], v[176:179], v[136:139], v[66:81]
	v_add_f32_e32 v86, v86, v240
	v_add_f32_e32 v87, v87, v224
	v_cvt_pk_bf16_f32 v94, v238, v239
	v_add_f32_e32 v86, v86, v241
	v_add_f32_e32 v87, v87, v225
	v_cvt_pk_bf16_f32 v95, v240, v241
	v_add_f32_e32 v86, v86, v244
	v_add_f32_e32 v87, v87, v226
	v_cvt_pk_bf16_f32 v96, v244, v245
	v_add_f32_e32 v86, v86, v245
	v_add_f32_e32 v87, v87, v227
	v_cvt_pk_bf16_f32 v97, v246, v247
	v_add_f32_e32 v86, v86, v246
	v_add_f32_e32 v87, v87, v228
	s_nop 0
	v_add_f32_e32 v86, v86, v247
	v_add_f32_e32 v87, v87, v229
	v_add_f32_e32 v86, v86, v248
	v_add_f32_e32 v87, v87, v230
	v_mfma_f32_32x32x16_bf16 v[112:127], v[90:93], v[136:139], v[112:127]
	v_add_f32_e32 v86, v86, v249
	v_add_f32_e32 v87, v87, v231
	v_add_f32_e32 v86, v86, v250
	v_add_f32_e32 v87, v87, v232
	v_add_f32_e32 v86, v86, v251
	v_add_f32_e32 v87, v87, v233
	v_add_f32_e32 v86, v86, v252
	v_add_f32_e32 v87, v87, v234
	v_add_f32_e32 v86, v86, v253
	v_add_f32_e32 v87, v87, v235
	v_add_f32_e32 v86, v86, v254
	v_add_f32_e32 v87, v87, v236
	v_add_f32_e32 v86, v86, v255
	v_add_f32_e32 v87, v87, v237
	v_add_f32_e32 v86, v86, v87
	v_add_f32_e32 v216, v216, v86
	v_mfma_f32_32x32x16_bf16 v[66:81], v[196:199], v[140:143], v[66:81]
	v_cvt_pk_bf16_f32 v98, v248, v249
	v_cvt_pk_bf16_f32 v99, v250, v251
	v_cvt_pk_bf16_f32 v100, v252, v253
	v_cvt_pk_bf16_f32 v101, v254, v255
	v_cvt_pk_bf16_f32 v102, v222, v223
	v_cvt_pk_bf16_f32 v103, v224, v225
	v_cvt_pk_bf16_f32 v104, v226, v227
	v_cvt_pk_bf16_f32 v105, v228, v229
	v_cvt_pk_bf16_f32 v106, v230, v231
	v_cvt_pk_bf16_f32 v107, v232, v233
	v_cvt_pk_bf16_f32 v108, v234, v235
	v_cvt_pk_bf16_f32 v109, v236, v237
	v_mfma_f32_32x32x16_bf16 v[112:127], v[192:195], v[140:143], v[112:127]
	ds_read_b64_tr_b16 v[82:83], v184 offset:0
	ds_read_b64_tr_b16 v[84:85], v184 offset:0x800
	ds_read_b64_tr_b16 v[86:87], v184 offset:0x1000
	ds_read_b64_tr_b16 v[88:89], v184 offset:0x1800
	ds_read_b64_tr_b16 v[90:91], v184 offset:0x2000
	ds_read_b64_tr_b16 v[92:93], v184 offset:0x2800
	ds_read_b64_tr_b16 v[176:177], v184 offset:0x3000
	ds_read_b64_tr_b16 v[178:179], v184 offset:0x3800
	ds_read_b64_tr_b16 v[192:193], v184 offset:0x200
	ds_read_b64_tr_b16 v[194:195], v184 offset:0xa00
	ds_read_b64_tr_b16 v[196:197], v184 offset:0x1200
	ds_read_b64_tr_b16 v[198:199], v184 offset:0x1a00
	ds_read_b64_tr_b16 v[200:201], v184 offset:0x2200
	ds_read_b64_tr_b16 v[202:203], v184 offset:0x2a00
	ds_read_b64_tr_b16 v[204:205], v184 offset:0x3200
	ds_read_b64_tr_b16 v[206:207], v184 offset:0x3a00
	s_waitcnt lgkmcnt(8)
	s_nop 0
	v_mfma_f32_32x32x16_bf16 v[2:17], v[94:97], v[82:85], v[2:17]
	v_exp_f32_e32 v222, v66
	s_nop 3
	v_exp_f32_e32 v1, v113
	v_exp_f32_e32 v82, v114
	v_exp_f32_e32 v83, v115
	v_mfma_f32_32x32x16_bf16 v[2:17], v[98:101], v[86:89], v[2:17]
	v_exp_f32_e32 v223, v67
	v_exp_f32_e32 v88, v112
	v_mfma_f32_32x32x16_bf16 v[2:17], v[102:105], v[90:93], v[2:17]
	v_exp_f32_e32 v224, v68
	v_mfma_f32_32x32x16_bf16 v[2:17], v[106:109], v[176:179], v[2:17]
	v_exp_f32_e32 v225, v69
	ds_read_b64_tr_b16 v[90:91], v184 offset:0x400
	ds_read_b64_tr_b16 v[92:93], v184 offset:0xc00
	ds_read_b64_tr_b16 v[110:111], v184 offset:0x1400
	ds_read_b64_tr_b16 v[112:113], v184 offset:0x1c00
	ds_read_b64_tr_b16 v[176:177], v184 offset:0x2400
	ds_read_b64_tr_b16 v[178:179], v184 offset:0x2c00
	ds_read_b64_tr_b16 v[208:209], v184 offset:0x3400
	ds_read_b64_tr_b16 v[210:211], v184 offset:0x3c00
	s_waitcnt lgkmcnt(8)
	v_mfma_f32_32x32x16_bf16 v[18:33], v[94:97], v[192:195], v[18:33]
	v_exp_f32_e32 v226, v70
	v_exp_f32_e32 v84, v116
	v_exp_f32_e32 v85, v117
	v_exp_f32_e32 v86, v118
	v_exp_f32_e32 v87, v119
	v_mfma_f32_32x32x16_bf16 v[18:33], v[98:101], v[196:199], v[18:33]
	v_exp_f32_e32 v227, v71
	v_mfma_f32_32x32x16_bf16 v[18:33], v[102:105], v[200:203], v[18:33]
	v_exp_f32_e32 v228, v72
	v_mfma_f32_32x32x16_bf16 v[18:33], v[106:109], v[204:207], v[18:33]
	v_exp_f32_e32 v229, v73
	ds_read_b64_tr_b16 v[114:115], v184 offset:0x600
	ds_read_b64_tr_b16 v[116:117], v184 offset:0xe00
	ds_read_b64_tr_b16 v[192:193], v184 offset:0x1600
	ds_read_b64_tr_b16 v[194:195], v184 offset:0x1e00
	ds_read_b64_tr_b16 v[196:197], v184 offset:0x2600
	ds_read_b64_tr_b16 v[198:199], v184 offset:0x2e00
	ds_read_b64_tr_b16 v[200:201], v184 offset:0x3600
	ds_read_b64_tr_b16 v[202:203], v184 offset:0x3e00
	s_waitcnt lgkmcnt(8)
	v_mfma_f32_32x32x16_bf16 v[34:49], v[94:97], v[90:93], v[34:49]
	v_exp_f32_e32 v230, v74
	v_exp_f32_e32 v90, v120
	v_exp_f32_e32 v89, v121
	v_exp_f32_e32 v92, v122
	v_exp_f32_e32 v91, v123
	v_mfma_f32_32x32x16_bf16 v[34:49], v[98:101], v[110:113], v[34:49]
	v_exp_f32_e32 v231, v75
	v_mfma_f32_32x32x16_bf16 v[34:49], v[102:105], v[176:179], v[34:49]
	v_exp_f32_e32 v232, v76
	v_mfma_f32_32x32x16_bf16 v[34:49], v[106:109], v[208:211], v[34:49]
	v_exp_f32_e32 v233, v77
	s_waitcnt lgkmcnt(0)
	v_mfma_f32_32x32x16_bf16 v[50:65], v[94:97], v[114:117], v[50:65]
	v_exp_f32_e32 v234, v78
	v_exp_f32_e32 v94, v124
	v_exp_f32_e32 v93, v125
	v_exp_f32_e32 v95, v126
	v_exp_f32_e32 v151, v127
	v_mfma_f32_32x32x16_bf16 v[50:65], v[98:101], v[192:195], v[50:65]
	v_exp_f32_e32 v235, v79
	v_mfma_f32_32x32x16_bf16 v[50:65], v[102:105], v[196:199], v[50:65]
	v_exp_f32_e32 v236, v80
	v_mfma_f32_32x32x16_bf16 v[50:65], v[106:109], v[200:203], v[50:65]
	v_exp_f32_e32 v237, v81
	s_waitcnt vmcnt(0)
	s_add_u32 s4, s4, 0x180000
	s_addc_u32 s5, s5, 0
	s_add_i32 s16, s16, 2
	s_and_b64 vcc, exec, s[0:1]
	s_waitcnt vmcnt(0)
	s_barrier
	s_cbranch_vccnz .LBB0_911

.LBB0_909:
	v_lshl_add_u64 v[178:179], s[4:5], 0, v[172:173]
	s_mov_b32 m0, s30
	v_lshl_add_u64 v[96:97], v[178:179], 0, s[8:9]
	v_lshl_add_u64 v[176:177], s[4:5], 0, v[174:175]
	global_load_lds_dwordx4 v[96:97], off
	v_lshl_add_u64 v[96:97], v[176:177], 0, s[8:9]
	s_mov_b32 m0, s33
	s_nop 0
	global_load_lds_dwordx4 v[96:97], off
	ds_read_b128 v[96:99], v188 offset:32768
	ds_read_b128 v[100:103], v188 offset:36864
	ds_read_b128 v[192:195], v189 offset:32768
	ds_read_b128 v[196:199], v189 offset:36864
	ds_read_b128 v[200:203], v190 offset:32768
	ds_read_b128 v[204:207], v190 offset:36864
	ds_read_b128 v[208:211], v191 offset:32768
	ds_read_b128 v[212:215], v191 offset:36864
	s_waitcnt lgkmcnt(0)
	v_mfma_f32_32x32x16_bf16 v[112:127], v[96:99], v[128:131], 0
	v_mfma_f32_32x32x16_bf16 v[96:111], v[100:103], v[128:131], 0
	v_mfma_f32_32x32x16_bf16 v[112:127], v[192:195], v[132:135], v[112:127]
	v_mfma_f32_32x32x16_bf16 v[96:111], v[196:199], v[132:135], v[96:111]
	v_add_f32_e32 v67, v88, v1
	v_cvt_pk_bf16_f32 v66, v88, v1
	v_add_f32_e32 v1, v222, v223
	v_add_f32_e32 v67, v67, v82
	v_mfma_f32_32x32x16_bf16 v[112:127], v[200:203], v[136:139], v[112:127]
	v_add_f32_e32 v1, v1, v224
	v_add_f32_e32 v67, v67, v83
	v_cvt_pk_bf16_f32 v68, v84, v85
	v_add_f32_e32 v1, v1, v225
	v_add_f32_e32 v67, v67, v84
	v_cvt_pk_bf16_f32 v69, v86, v87
	v_add_f32_e32 v1, v1, v226
	v_add_f32_e32 v67, v67, v85
	v_mfma_f32_32x32x16_bf16 v[96:111], v[204:207], v[136:139], v[96:111]
	v_add_f32_e32 v1, v1, v227
	v_add_f32_e32 v67, v67, v86
	v_add_f32_e32 v1, v1, v228
	v_add_f32_e32 v67, v67, v87
	v_add_f32_e32 v1, v1, v229
	v_add_f32_e32 v67, v67, v90
	v_add_f32_e32 v1, v1, v230
	v_add_f32_e32 v67, v67, v89
	v_add_f32_e32 v1, v1, v231
	v_add_f32_e32 v67, v67, v92
	v_add_f32_e32 v1, v1, v232
	v_add_f32_e32 v67, v67, v91
	v_add_f32_e32 v1, v1, v233
	v_add_f32_e32 v67, v67, v94
	v_add_f32_e32 v1, v1, v234
	v_add_f32_e32 v67, v67, v93
	v_add_f32_e32 v1, v1, v235
	v_add_f32_e32 v67, v67, v95
	v_add_f32_e32 v1, v1, v236
	v_add_f32_e32 v67, v67, v151
	v_add_f32_e32 v1, v1, v237
	v_add_f32_e32 v1, v67, v1
	v_cvt_pk_bf16_f32 v67, v82, v83
	v_mfma_f32_32x32x16_bf16 v[112:127], v[208:211], v[140:143], v[112:127]
	v_cvt_pk_bf16_f32 v72, v90, v89
	v_cvt_pk_bf16_f32 v73, v92, v91
	v_cvt_pk_bf16_f32 v74, v94, v93
	v_cvt_pk_bf16_f32 v75, v95, v151
	v_cvt_pk_bf16_f32 v76, v222, v223
	v_cvt_pk_bf16_f32 v77, v224, v225
	v_cvt_pk_bf16_f32 v78, v226, v227
	v_mfma_f32_32x32x16_bf16 v[96:111], v[212:215], v[140:143], v[96:111]
	v_cvt_pk_bf16_f32 v79, v228, v229
	v_cvt_pk_bf16_f32 v80, v230, v231
	v_cvt_pk_bf16_f32 v81, v232, v233
	v_cvt_pk_bf16_f32 v82, v234, v235
	v_cvt_pk_bf16_f32 v83, v236, v237
	ds_read_b64_tr_b16 v[84:85], v185 offset:0
	ds_read_b64_tr_b16 v[86:87], v185 offset:0x800
	ds_read_b64_tr_b16 v[88:89], v185 offset:0x1000
	ds_read_b64_tr_b16 v[90:91], v185 offset:0x1800
	ds_read_b64_tr_b16 v[92:93], v185 offset:0x2000
	ds_read_b64_tr_b16 v[94:95], v185 offset:0x2800
	ds_read_b64_tr_b16 v[192:193], v185 offset:0x3000
	ds_read_b64_tr_b16 v[194:195], v185 offset:0x3800
	ds_read_b64_tr_b16 v[196:197], v185 offset:0x200
	ds_read_b64_tr_b16 v[198:199], v185 offset:0xa00
	ds_read_b64_tr_b16 v[200:201], v185 offset:0x1200
	ds_read_b64_tr_b16 v[202:203], v185 offset:0x1a00
	ds_read_b64_tr_b16 v[204:205], v185 offset:0x2200
	ds_read_b64_tr_b16 v[206:207], v185 offset:0x2a00
	ds_read_b64_tr_b16 v[208:209], v185 offset:0x3200
	ds_read_b64_tr_b16 v[210:211], v185 offset:0x3a00
	s_waitcnt lgkmcnt(8)
	s_nop 0
	v_mfma_f32_32x32x16_bf16 v[2:17], v[66:69], v[84:87], v[2:17]
	v_exp_f32_e32 v238, v112
	v_exp_f32_e32 v239, v113
	v_mfma_f32_32x32x16_bf16 v[2:17], v[72:75], v[88:91], v[2:17]
	v_exp_f32_e32 v240, v114
	v_exp_f32_e32 v241, v115
	v_mfma_f32_32x32x16_bf16 v[2:17], v[76:79], v[92:95], v[2:17]
	v_exp_f32_e32 v244, v116
	v_exp_f32_e32 v245, v117
	v_mfma_f32_32x32x16_bf16 v[2:17], v[80:83], v[192:195], v[2:17]
	v_exp_f32_e32 v246, v118
	v_exp_f32_e32 v247, v119
	ds_read_b64_tr_b16 v[84:85], v185 offset:0x400
	ds_read_b64_tr_b16 v[86:87], v185 offset:0xc00
	ds_read_b64_tr_b16 v[88:89], v185 offset:0x1400
	ds_read_b64_tr_b16 v[90:91], v185 offset:0x1c00
	ds_read_b64_tr_b16 v[92:93], v185 offset:0x2400
	ds_read_b64_tr_b16 v[94:95], v185 offset:0x2c00
	ds_read_b64_tr_b16 v[192:193], v185 offset:0x3400
	ds_read_b64_tr_b16 v[194:195], v185 offset:0x3c00
	s_waitcnt lgkmcnt(8)
	v_mfma_f32_32x32x16_bf16 v[18:33], v[66:69], v[196:199], v[18:33]
	v_exp_f32_e32 v248, v120
	v_exp_f32_e32 v249, v121
	v_mfma_f32_32x32x16_bf16 v[18:33], v[72:75], v[200:203], v[18:33]
	v_exp_f32_e32 v250, v122
	v_exp_f32_e32 v251, v123
	v_mfma_f32_32x32x16_bf16 v[18:33], v[76:79], v[204:207], v[18:33]
	v_exp_f32_e32 v252, v124
	v_exp_f32_e32 v253, v125
	v_mfma_f32_32x32x16_bf16 v[18:33], v[80:83], v[208:211], v[18:33]
	v_exp_f32_e32 v254, v126
	v_exp_f32_e32 v255, v127
	ds_read_b64_tr_b16 v[196:197], v185 offset:0x600
	ds_read_b64_tr_b16 v[198:199], v185 offset:0xe00
	ds_read_b64_tr_b16 v[200:201], v185 offset:0x1600
	ds_read_b64_tr_b16 v[202:203], v185 offset:0x1e00
	ds_read_b64_tr_b16 v[204:205], v185 offset:0x2600
	ds_read_b64_tr_b16 v[206:207], v185 offset:0x2e00
	ds_read_b64_tr_b16 v[208:209], v185 offset:0x3600
	ds_read_b64_tr_b16 v[210:211], v185 offset:0x3e00
	s_waitcnt lgkmcnt(8)
	v_mfma_f32_32x32x16_bf16 v[34:49], v[66:69], v[84:87], v[34:49]
	v_exp_f32_e32 v222, v96
	v_exp_f32_e32 v223, v97
	v_mfma_f32_32x32x16_bf16 v[34:49], v[72:75], v[88:91], v[34:49]
	v_exp_f32_e32 v224, v98
	v_exp_f32_e32 v225, v99
	v_mfma_f32_32x32x16_bf16 v[34:49], v[76:79], v[92:95], v[34:49]
	v_exp_f32_e32 v226, v100
	v_exp_f32_e32 v227, v101
	v_mfma_f32_32x32x16_bf16 v[34:49], v[80:83], v[192:195], v[34:49]
	v_exp_f32_e32 v228, v102
	v_exp_f32_e32 v229, v103
	s_waitcnt lgkmcnt(0)
	v_mfma_f32_32x32x16_bf16 v[50:65], v[66:69], v[196:199], v[50:65]
	v_exp_f32_e32 v230, v104
	v_exp_f32_e32 v231, v105
	v_mfma_f32_32x32x16_bf16 v[50:65], v[72:75], v[200:203], v[50:65]
	v_exp_f32_e32 v232, v106
	v_exp_f32_e32 v233, v107
	v_mfma_f32_32x32x16_bf16 v[50:65], v[76:79], v[204:207], v[50:65]
	v_exp_f32_e32 v234, v108
	v_exp_f32_e32 v235, v109
	v_mfma_f32_32x32x16_bf16 v[50:65], v[80:83], v[208:211], v[50:65]
	v_exp_f32_e32 v236, v110
	v_exp_f32_e32 v237, v111
	s_waitcnt vmcnt(0)
	s_cmp_ge_u32 s16, s11
	s_cselect_b64 s[0:1], -1, 0
	s_and_b64 vcc, exec, s[0:1]
	s_waitcnt vmcnt(0)
	s_barrier
	s_cbranch_vccnz .LBB0_906
	s_mov_b64 s[18:19], 0x15c81800
	v_lshl_add_u64 v[66:67], v[180:181], 0, s[18:19]
	s_mov_b32 m0, s31
	s_nop 0
	global_load_lds_dwordx4 v[66:67], off
	s_branch .LBB0_906
.LBB0_911:
	v_exp_f32_e32 v96, v66
	v_add_f32_e32 v66, 0, v88
	v_add_f32_e32 v66, v1, v66
	v_add_f32_e32 v66, v66, v82
	v_add_f32_e32 v66, v83, v66
	v_add_f32_e32 v66, v66, v84
	v_add_f32_e32 v66, v85, v66
	v_add_f32_e32 v66, v66, v86
	v_add_f32_e32 v66, v87, v66
	v_add_f32_e32 v66, v66, v90
	v_add_f32_e32 v66, v89, v66
	v_add_f32_e32 v66, v66, v92
	v_add_f32_e32 v66, v91, v66
	v_add_f32_e32 v66, v66, v94
	v_exp_f32_e32 v97, v67
	v_add_f32_e32 v66, v93, v66
	v_exp_f32_e32 v98, v68
	v_add_f32_e32 v66, v66, v95
	v_exp_f32_e32 v99, v69
	v_add_f32_e32 v66, v151, v66
	v_exp_f32_e32 v100, v70
	v_add_f32_e32 v66, v96, v66
	v_exp_f32_e32 v101, v71
	v_add_f32_e32 v66, v97, v66
	v_exp_f32_e32 v102, v72
	v_add_f32_e32 v66, v98, v66
	v_exp_f32_e32 v103, v73
	v_add_f32_e32 v66, v99, v66
	v_exp_f32_e32 v104, v74
	v_add_f32_e32 v66, v100, v66
	v_exp_f32_e32 v105, v75
	v_add_f32_e32 v66, v101, v66
	v_exp_f32_e32 v106, v76
	v_add_f32_e32 v66, v102, v66
	v_exp_f32_e32 v107, v77
	v_add_f32_e32 v66, v103, v66
	v_exp_f32_e32 v108, v78
	v_add_f32_e32 v66, v104, v66
	v_exp_f32_e32 v109, v79
	v_add_f32_e32 v66, v105, v66
	v_exp_f32_e32 v110, v80
	v_add_f32_e32 v66, v106, v66
	v_exp_f32_e32 v111, v81
	v_add_f32_e32 v66, v107, v66
	v_add_f32_e32 v66, v108, v66
	v_add_f32_e32 v66, v109, v66
	v_add_f32_e32 v66, v110, v66
	s_lshl_b32 s0, s10, 2
	v_add_f32_e32 v66, v111, v66
	v_readlane_b32 s44, v243, 63
	s_add_i32 s4, s0, 0
	v_mov_b32_e32 v67, v66
	v_readlane_b32 s45, v242, 0
	v_readlane_b32 s46, v242, 1
	v_readlane_b32 s47, v242, 2
	v_readlane_b32 s48, v242, 3
	v_readlane_b32 s49, v242, 4
	v_readlane_b32 s50, v242, 5
	v_readlane_b32 s51, v242, 6
	v_readlane_b32 s52, v242, 7
	v_readlane_b32 s53, v242, 8
	v_readlane_b32 s54, v242, 9
	v_readlane_b32 s55, v242, 10
	v_readlane_b32 s56, v242, 11
	v_readlane_b32 s57, v242, 12
	v_readlane_b32 s58, v242, 13
	v_readlane_b32 s59, v242, 14
	s_add_i32 s4, s4, 0x1e000
	v_permlane32_swap_b32_e32 v66, v67
	v_cvt_pk_bf16_f32 v68, v88, v1
	v_cvt_pk_bf16_f32 v69, v82, v83
	v_cvt_pk_bf16_f32 v70, v84, v85
	v_cvt_pk_bf16_f32 v71, v86, v87
	v_cvt_pk_bf16_f32 v72, v90, v89
	v_cvt_pk_bf16_f32 v73, v92, v91
	v_cvt_pk_bf16_f32 v74, v94, v93
	v_cvt_pk_bf16_f32 v75, v95, v151
	v_cvt_pk_bf16_f32 v76, v96, v97
	v_cvt_pk_bf16_f32 v77, v98, v99
	v_cvt_pk_bf16_f32 v78, v100, v101
	v_cvt_pk_bf16_f32 v79, v102, v103
	v_cvt_pk_bf16_f32 v80, v104, v105
	v_cvt_pk_bf16_f32 v81, v106, v107
	v_cvt_pk_bf16_f32 v82, v108, v109
	v_cvt_pk_bf16_f32 v83, v110, v111
	ds_read_b64_tr_b16 v[84:85], v185 offset:0
	ds_read_b64_tr_b16 v[86:87], v185 offset:0x800
	ds_read_b64_tr_b16 v[88:89], v185 offset:0x1000
	ds_read_b64_tr_b16 v[90:91], v185 offset:0x1800
	ds_read_b64_tr_b16 v[92:93], v185 offset:0x2000
	ds_read_b64_tr_b16 v[94:95], v185 offset:0x2800
	ds_read_b64_tr_b16 v[96:97], v185 offset:0x3000
	ds_read_b64_tr_b16 v[98:99], v185 offset:0x3800
	s_waitcnt lgkmcnt(0)
	s_nop 0
	v_mfma_f32_32x32x16_bf16 v[2:17], v[68:71], v[84:87], v[2:17]
	ds_read_b64_tr_b16 v[84:85], v185 offset:0x200
	ds_read_b64_tr_b16 v[86:87], v185 offset:0xa00
	v_mfma_f32_32x32x16_bf16 v[2:17], v[72:75], v[88:91], v[2:17]
	ds_read_b64_tr_b16 v[88:89], v185 offset:0x1200
	ds_read_b64_tr_b16 v[90:91], v185 offset:0x1a00
	v_mfma_f32_32x32x16_bf16 v[2:17], v[76:79], v[92:95], v[2:17]
	ds_read_b64_tr_b16 v[92:93], v185 offset:0x2200
	ds_read_b64_tr_b16 v[94:95], v185 offset:0x2a00
	ds_read_b64_tr_b16 v[100:101], v185 offset:0x3200
	ds_read_b64_tr_b16 v[102:103], v185 offset:0x3a00
	s_waitcnt lgkmcnt(0)
	v_mfma_f32_32x32x16_bf16 v[2:17], v[80:83], v[96:99], v[2:17]
	v_mfma_f32_32x32x16_bf16 v[18:33], v[68:71], v[84:87], v[18:33]
	ds_read_b64_tr_b16 v[84:85], v185 offset:0x400
	ds_read_b64_tr_b16 v[86:87], v185 offset:0xc00
	v_mfma_f32_32x32x16_bf16 v[18:33], v[72:75], v[88:91], v[18:33]
	ds_read_b64_tr_b16 v[88:89], v185 offset:0x1400
	ds_read_b64_tr_b16 v[90:91], v185 offset:0x1c00
	v_mfma_f32_32x32x16_bf16 v[18:33], v[76:79], v[92:95], v[18:33]
	ds_read_b64_tr_b16 v[92:93], v185 offset:0x2400
	ds_read_b64_tr_b16 v[94:95], v185 offset:0x2c00
	ds_read_b64_tr_b16 v[96:97], v185 offset:0x3400
	ds_read_b64_tr_b16 v[98:99], v185 offset:0x3c00
	s_waitcnt lgkmcnt(0)
	v_mfma_f32_32x32x16_bf16 v[18:33], v[80:83], v[100:103], v[18:33]
	v_mfma_f32_32x32x16_bf16 v[34:49], v[68:71], v[84:87], v[34:49]
	ds_read_b64_tr_b16 v[84:85], v185 offset:0x600
	ds_read_b64_tr_b16 v[86:87], v185 offset:0xe00
	v_mfma_f32_32x32x16_bf16 v[34:49], v[72:75], v[88:91], v[34:49]
	ds_read_b64_tr_b16 v[88:89], v185 offset:0x1600
	ds_read_b64_tr_b16 v[90:91], v185 offset:0x1e00
	v_mfma_f32_32x32x16_bf16 v[34:49], v[76:79], v[92:95], v[34:49]
	ds_read_b64_tr_b16 v[92:93], v185 offset:0x2600
	ds_read_b64_tr_b16 v[94:95], v185 offset:0x2e00
	ds_read_b64_tr_b16 v[100:101], v185 offset:0x3600
	ds_read_b64_tr_b16 v[102:103], v185 offset:0x3e00
	s_waitcnt lgkmcnt(0)
	v_mfma_f32_32x32x16_bf16 v[34:49], v[80:83], v[96:99], v[34:49]
	v_mfma_f32_32x32x16_bf16 v[50:65], v[68:71], v[84:87], v[50:65]
	s_barrier
	v_mfma_f32_32x32x16_bf16 v[50:65], v[72:75], v[88:91], v[50:65]
	v_mfma_f32_32x32x16_bf16 v[50:65], v[76:79], v[92:95], v[50:65]
	v_mfma_f32_32x32x16_bf16 v[50:65], v[80:83], v[100:103], v[50:65]
	v_mov_b32_e32 v217, v216
	s_nop 1
	v_permlane32_swap_b32_e32 v216, v217
	v_add_f32_e32 v216, v216, v217
	s_and_saveexec_b64 s[0:1], s[2:3]
	s_cbranch_execz .LBB0_897
	v_add_f32_e32 v1, v66, v67
	v_add_f32_e32 v1, v149, v1
	v_add_f32_e32 v1, v1, v216
	v_lshl_add_u32 v66, v165, 2, s4
	ds_write_b32 v66, v1
	s_branch .LBB0_897

.LBB0_2318:
	v_mov_b32_e32 v219, 0
	s_lshl_b32 s0, s30, 1
	s_and_b32 s24, s0, 0x700
	s_ashr_i32 s0, s30, 10
	s_ashr_i32 s1, s0, 31
	s_lshl_b64 s[46:47], s[0:1], 14
	s_lshl_b32 s1, s30, 8
	s_and_b32 s1, s1, 0x3f00
	s_or_b32 s46, s46, s1
	s_bfe_u32 s23, s30, 0x40006
	s_mul_i32 s4, s47, 0x3000
	s_mul_hi_u32 s21, s46, 0x3000
	s_lshl_b32 s52, s23, 7
	s_lshl_b32 s1, s0, 8
	s_add_i32 s21, s21, s4
	s_mul_i32 s4, s46, 0x3000
	v_readlane_b32 s40, v242, 17
	v_readlane_b32 s41, v242, 18
	s_add_u32 s4, s40, s4
	s_addc_u32 s21, s41, s21
	s_add_u32 s4, s4, s52
	s_addc_u32 s21, s21, 0
	s_add_u32 s28, s4, 0x1000
	s_addc_u32 s29, s21, 0
	s_mul_i32 s4, s0, 0x300000
	s_mul_hi_i32 s1, s1, 0x3000
	s_add_u32 s4, s40, s4
	s_addc_u32 s21, s41, s1
	s_add_u32 s34, s4, s52
	s_addc_u32 s35, s21, 0
	s_mul_i32 s58, s0, 0xc000000
	s_mul_hi_i32 s25, s0, 0xc000000
	s_add_u32 s0, s40, s58
	s_addc_u32 s1, s41, s25
	s_add_u32 s0, s0, s52
	s_addc_u32 s1, s1, 0
	s_and_b32 s31, s52, 0x700
	s_add_u32 s61, s4, s31
	s_addc_u32 s62, s21, 0
	s_add_u32 s40, s61, 0x18002000
	v_readfirstlane_b32 s33, v0
	s_addc_u32 s41, s62, 0
	s_lshr_b32 s31, s33, 6
	s_lshl_b32 s4, s31, 5
	v_or_b32_e32 v4, s4, v165
	v_mov_b64_e32 v[2:3], s[28:29]
	v_mad_u64_u32 v[2:3], s[28:29], v4, s20, v[2:3]
	v_lshl_add_u64 v[2:3], v[2:3], 0, v[132:133]
	global_load_dwordx4 v[114:117], v[2:3], off
	global_load_dwordx4 v[118:121], v[2:3], off offset:32
	global_load_dwordx4 v[122:125], v[2:3], off offset:64
	global_load_dwordx4 v[126:129], v[2:3], off offset:96
	s_andn2_b32 s33, s33, 63
	s_ashr_i32 s21, s33, 4
	s_and_b32 s28, s21, -16
	s_lshr_b32 s21, s21, 1
	s_and_b32 s21, s21, 4
	v_or_b32_e32 v2, s33, v166
	s_or_b32 s60, s28, s21
	s_add_i32 s21, s33, 0x200
	v_ashrrev_i32_e32 v3, 31, v2
	s_ashr_i32 s21, s21, 4
	v_lshrrev_b32_e32 v3, 29, v3
	s_and_b32 s28, s21, -16
	s_lshr_b32 s21, s21, 1
	v_add_u32_e32 v3, v2, v3
	s_and_b32 s21, s21, 4
	v_ashrrev_i32_e32 v5, 3, v3
	v_and_b32_e32 v3, 0x1ffffff8, v3
	s_or_b32 s59, s28, s21
	v_sub_u32_e32 v3, v2, v3
	v_lshrrev_b32_e32 v4, 1, v5
	v_and_b32_e32 v137, 0x60, v2
	v_or_b32_e32 v2, s60, v163
	v_or_b32_e32 v6, s59, v163
	v_bitop3_b32 v3, v4, v3, 7 bitop3:0x6c
	v_or_b32_e32 v4, v137, v162
	v_lshrrev_b32_e32 v7, 1, v2
	v_xor_b32_e32 v7, v7, v2
	v_and_b32_e32 v7, 4, v7
	v_lshl_or_b32 v7, v7, 1, v7
	v_xor_b32_e32 v2, v2, v7
	v_lshrrev_b32_e32 v7, 1, v6
	v_xor_b32_e32 v7, v7, v6
	v_and_b32_e32 v7, 4, v7
	v_lshl_or_b32 v7, v7, 1, v7
	v_xor_b32_e32 v6, v6, v7
	v_mul_lo_u32 v2, v2, s22
	v_mul_lo_u32 v6, v6, s22
	v_mul_lo_u32 v5, v5, s22
	v_or_b32_e32 v2, v2, v4
	v_or_b32_e32 v4, v6, v4
	v_lshl_add_u32 v6, v3, 3, v5
	v_ashrrev_i32_e32 v7, 31, v6
	v_lshlrev_b64 v[150:151], 1, v[6:7]
	s_lshl_b32 s21, s31, 10
	v_lshl_add_u64 v[98:99], s[34:35], 0, v[150:151]
	s_add_i32 s34, s21, 0
	s_add_i32 s35, s34, 0x8000
	v_ashrrev_i32_e32 v3, 31, v2
	v_lshl_add_u64 v[6:7], v[98:99], 0, s[6:7]
	s_mov_b32 m0, s35
	v_lshlrev_b64 v[152:153], 1, v[2:3]
	v_ashrrev_i32_e32 v5, 31, v4
	global_load_lds_dwordx4 v[6:7], off
	v_lshl_add_u64 v[2:3], s[40:41], 0, v[152:153]
	s_mov_b32 m0, s34
	v_lshlrev_b64 v[154:155], 1, v[4:5]
	s_add_i32 s54, s34, 0x2000
	global_load_lds_dwordx4 v[2:3], off
	v_lshl_add_u64 v[2:3], s[40:41], 0, v[154:155]
	s_mov_b32 m0, s54
	s_add_i32 s55, s34, 0xa000
	global_load_lds_dwordx4 v[2:3], off
	v_lshl_add_u64 v[2:3], v[98:99], 0, s[8:9]
	s_mov_b32 m0, s55
	s_waitcnt vmcnt(0)
	s_waitcnt vmcnt(0) lgkmcnt(0)
	s_barrier
	global_load_lds_dwordx4 v[2:3], off
	ds_read_b128 v[2:5], v172 offset:32768
	ds_read_b128 v[18:21], v172 offset:36864
	s_waitcnt lgkmcnt(0)
	v_mfma_f32_32x32x16_bf16 v[2:17], v[2:5], v[114:117], 0
	ds_read_b128 v[22:25], v173 offset:32768
	ds_read_b128 v[34:37], v173 offset:36864
	s_add_u32 s28, s61, 0x180c2000
	v_lshl_add_u64 v[30:31], v[98:99], 0, s[12:13]
	s_mov_b32 m0, s35
	s_addc_u32 s29, s62, 0
	s_add_i32 s56, s34, 0x4000
	s_add_i32 s57, s34, 0x6000
	s_waitcnt lgkmcnt(0)
	v_mfma_f32_32x32x16_bf16 v[2:17], v[22:25], v[118:121], v[2:17]
	ds_read_b128 v[22:25], v174 offset:32768
	ds_read_b128 v[38:41], v174 offset:36864
	ds_read_b128 v[26:29], v175 offset:32768
	ds_read_b128 v[42:45], v175 offset:36864
	s_waitcnt vmcnt(0)
	s_waitcnt vmcnt(0) lgkmcnt(0)
	s_barrier
	global_load_lds_dwordx4 v[30:31], off
	v_mfma_f32_32x32x16_bf16 v[2:17], v[22:25], v[122:125], v[2:17]
	v_lshl_add_u64 v[22:23], s[28:29], 0, v[152:153]
	s_mov_b32 m0, s56
	s_mov_b32 s53, s5
	global_load_lds_dwordx4 v[22:23], off
	v_lshl_add_u64 v[22:23], s[28:29], 0, v[154:155]
	s_mov_b32 m0, s57
	v_mfma_f32_32x32x16_bf16 v[2:17], v[26:29], v[126:129], v[2:17]
	global_load_lds_dwordx4 v[22:23], off
	v_mfma_f32_32x32x16_bf16 v[18:33], v[18:21], v[114:117], 0
	s_nop 9
	v_exp_f32_e32 v54, v2
	v_exp_f32_e32 v55, v3
	v_exp_f32_e32 v56, v4
	v_exp_f32_e32 v57, v5
	v_exp_f32_e32 v58, v6
	v_exp_f32_e32 v59, v7
	v_exp_f32_e32 v60, v8
	v_mfma_f32_32x32x16_bf16 v[18:33], v[34:37], v[118:121], v[18:33]
	v_exp_f32_e32 v61, v9
	v_exp_f32_e32 v62, v10
	v_exp_f32_e32 v63, v11
	v_exp_f32_e32 v64, v12
	v_exp_f32_e32 v65, v13
	v_exp_f32_e32 v102, v14
	v_exp_f32_e32 v103, v15
	v_mfma_f32_32x32x16_bf16 v[18:33], v[38:41], v[122:125], v[18:33]
	v_exp_f32_e32 v104, v16
	v_exp_f32_e32 v105, v17
	ds_read_b128 v[2:5], v172 offset:40960
	ds_read_b128 v[6:9], v172 offset:45056
	ds_read_b128 v[10:13], v173 offset:40960
	ds_read_b128 v[14:17], v173 offset:45056
	ds_read_b128 v[34:37], v174 offset:40960
	ds_read_b128 v[38:41], v174 offset:45056
	ds_read_b128 v[46:49], v175 offset:40960
	ds_read_b128 v[50:53], v175 offset:45056
	v_mfma_f32_32x32x16_bf16 v[18:33], v[42:45], v[126:129], v[18:33]
	s_waitcnt lgkmcnt(0)
	v_mfma_f32_32x32x16_bf16 v[66:81], v[6:9], v[114:117], 0
	v_mfma_f32_32x32x16_bf16 v[82:97], v[2:5], v[114:117], 0
	s_nop 8
	v_exp_f32_e32 v2, v18
	v_exp_f32_e32 v3, v19
	v_exp_f32_e32 v4, v20
	v_exp_f32_e32 v5, v21
	v_exp_f32_e32 v18, v22
	v_exp_f32_e32 v19, v23
	v_exp_f32_e32 v20, v24
	v_exp_f32_e32 v21, v25
	v_mfma_f32_32x32x16_bf16 v[66:81], v[14:17], v[118:121], v[66:81]
	v_exp_f32_e32 v6, v26
	v_exp_f32_e32 v7, v27
	v_exp_f32_e32 v8, v28
	v_exp_f32_e32 v9, v29
	v_mfma_f32_32x32x16_bf16 v[82:97], v[10:13], v[118:121], v[82:97]
	v_exp_f32_e32 v10, v30
	v_exp_f32_e32 v11, v31
	v_exp_f32_e32 v12, v32
	v_exp_f32_e32 v13, v33
	v_add_f32_e32 v14, v54, v55
	v_add_f32_e32 v15, v2, v3
	v_mfma_f32_32x32x16_bf16 v[66:81], v[38:41], v[122:125], v[66:81]
	v_add_f32_e32 v14, v14, v56
	v_add_f32_e32 v15, v15, v4
	v_cvt_pk_bf16_f32 v54, v54, v55
	v_add_f32_e32 v14, v14, v57
	v_add_f32_e32 v15, v15, v5
	v_cvt_pk_bf16_f32 v55, v56, v57
	v_add_f32_e32 v14, v14, v58
	v_add_f32_e32 v15, v15, v18
	v_cvt_pk_bf16_f32 v56, v58, v59
	v_add_f32_e32 v14, v14, v59
	v_add_f32_e32 v15, v15, v19
	v_cvt_pk_bf16_f32 v57, v60, v61
	v_add_f32_e32 v14, v14, v60
	v_add_f32_e32 v15, v15, v20
	s_nop 0
	v_add_f32_e32 v14, v14, v61
	v_add_f32_e32 v15, v15, v21
	v_add_f32_e32 v14, v14, v62
	v_add_f32_e32 v15, v15, v6
	v_mfma_f32_32x32x16_bf16 v[82:97], v[34:37], v[122:125], v[82:97]
	v_add_f32_e32 v14, v14, v63
	v_add_f32_e32 v15, v15, v7
	s_nop 0
	v_add_f32_e32 v14, v14, v64
	v_add_f32_e32 v15, v15, v8
	s_nop 0
	v_add_f32_e32 v14, v14, v65
	v_add_f32_e32 v15, v15, v9
	s_nop 0
	v_add_f32_e32 v14, v14, v102
	v_add_f32_e32 v15, v15, v10
	s_nop 0
	v_add_f32_e32 v14, v14, v103
	v_add_f32_e32 v15, v15, v11
	s_nop 0
	v_add_f32_e32 v14, v14, v104
	v_add_f32_e32 v15, v15, v12
	s_nop 0
	v_add_f32_e32 v14, v14, v105
	v_add_f32_e32 v15, v15, v13
	s_nop 0
	v_add_f32_e32 v14, v14, v15
	v_mov_b32_e32 v15, v14
	s_nop 1
	v_permlane32_swap_b32_e32 v14, v15
	v_add_f32_e32 v14, v14, v15
	v_add_f32_e32 v135, 0, v14
	v_mfma_f32_32x32x16_bf16 v[66:81], v[50:53], v[126:129], v[66:81]
	v_cvt_pk_bf16_f32 v100, v62, v63
	v_cvt_pk_bf16_f32 v101, v64, v65
	v_cvt_pk_bf16_f32 v102, v102, v103
	v_cvt_pk_bf16_f32 v103, v104, v105
	v_cvt_pk_bf16_f32 v104, v2, v3
	v_cvt_pk_bf16_f32 v105, v4, v5
	v_cvt_pk_bf16_f32 v106, v18, v19
	v_cvt_pk_bf16_f32 v107, v20, v21
	v_cvt_pk_bf16_f32 v108, v6, v7
	v_cvt_pk_bf16_f32 v109, v8, v9
	v_cvt_pk_bf16_f32 v110, v10, v11
	v_cvt_pk_bf16_f32 v111, v12, v13
	v_mfma_f32_32x32x16_bf16 v[82:97], v[46:49], v[126:129], v[82:97]
	ds_read_b64_tr_b16 v[2:3], v168 offset:0
	ds_read_b64_tr_b16 v[4:5], v168 offset:0x800
	ds_read_b64_tr_b16 v[18:19], v168 offset:0x1000
	ds_read_b64_tr_b16 v[20:21], v168 offset:0x1800
	ds_read_b64_tr_b16 v[22:23], v168 offset:0x2000
	ds_read_b64_tr_b16 v[24:25], v168 offset:0x2800
	ds_read_b64_tr_b16 v[26:27], v168 offset:0x3000
	ds_read_b64_tr_b16 v[28:29], v168 offset:0x3800
	ds_read_b64_tr_b16 v[30:31], v168 offset:0x200
	ds_read_b64_tr_b16 v[32:33], v168 offset:0xa00
	ds_read_b64_tr_b16 v[34:35], v168 offset:0x1200
	ds_read_b64_tr_b16 v[36:37], v168 offset:0x1a00
	ds_read_b64_tr_b16 v[38:39], v168 offset:0x2200
	ds_read_b64_tr_b16 v[40:41], v168 offset:0x2a00
	ds_read_b64_tr_b16 v[42:43], v168 offset:0x3200
	ds_read_b64_tr_b16 v[44:45], v168 offset:0x3a00
	s_waitcnt lgkmcnt(8)
	s_nop 0
	v_mfma_f32_32x32x16_bf16 v[2:17], v[54:57], v[2:5], 0
	s_nop 3
	v_exp_f32_e32 v139, v82
	v_exp_f32_e32 v141, v83
	v_exp_f32_e32 v143, v84
	v_exp_f32_e32 v145, v85
	v_mfma_f32_32x32x16_bf16 v[2:17], v[100:103], v[18:21], v[2:17]
	v_mfma_f32_32x32x16_bf16 v[2:17], v[104:107], v[22:25], v[2:17]
	v_mfma_f32_32x32x16_bf16 v[2:17], v[108:111], v[26:29], v[2:17]
	ds_read_b64_tr_b16 v[46:47], v168 offset:0x400
	ds_read_b64_tr_b16 v[48:49], v168 offset:0xc00
	ds_read_b64_tr_b16 v[50:51], v168 offset:0x1400
	ds_read_b64_tr_b16 v[52:53], v168 offset:0x1c00
	ds_read_b64_tr_b16 v[58:59], v168 offset:0x2400
	ds_read_b64_tr_b16 v[60:61], v168 offset:0x2c00
	ds_read_b64_tr_b16 v[62:63], v168 offset:0x3400
	ds_read_b64_tr_b16 v[64:65], v168 offset:0x3c00
	s_waitcnt lgkmcnt(8)
	v_mfma_f32_32x32x16_bf16 v[18:33], v[54:57], v[30:33], 0
	v_exp_f32_e32 v147, v86
	v_exp_f32_e32 v149, v87
	v_exp_f32_e32 v196, v88
	v_exp_f32_e32 v197, v89
	v_mfma_f32_32x32x16_bf16 v[18:33], v[100:103], v[34:37], v[18:33]
	v_mfma_f32_32x32x16_bf16 v[18:33], v[104:107], v[38:41], v[18:33]
	v_mfma_f32_32x32x16_bf16 v[18:33], v[108:111], v[42:45], v[18:33]
	ds_read_b64_tr_b16 v[82:83], v168 offset:0x600
	ds_read_b64_tr_b16 v[84:85], v168 offset:0xe00
	ds_read_b64_tr_b16 v[86:87], v168 offset:0x1600
	ds_read_b64_tr_b16 v[88:89], v168 offset:0x1e00
	ds_read_b64_tr_b16 v[156:157], v168 offset:0x2600
	ds_read_b64_tr_b16 v[158:159], v168 offset:0x2e00
	ds_read_b64_tr_b16 v[176:177], v168 offset:0x3600
	ds_read_b64_tr_b16 v[178:179], v168 offset:0x3e00
	s_waitcnt lgkmcnt(8)
	v_mfma_f32_32x32x16_bf16 v[34:49], v[54:57], v[46:49], 0
	v_exp_f32_e32 v198, v90
	v_exp_f32_e32 v199, v91
	v_exp_f32_e32 v200, v92
	v_exp_f32_e32 v201, v93
	v_mfma_f32_32x32x16_bf16 v[34:49], v[100:103], v[50:53], v[34:49]
	v_mfma_f32_32x32x16_bf16 v[34:49], v[104:107], v[58:61], v[34:49]
	v_mfma_f32_32x32x16_bf16 v[34:49], v[108:111], v[62:65], v[34:49]
	s_waitcnt lgkmcnt(0)
	v_mfma_f32_32x32x16_bf16 v[50:65], v[54:57], v[82:85], 0
	v_exp_f32_e32 v202, v94
	v_exp_f32_e32 v203, v95
	v_exp_f32_e32 v204, v96
	v_exp_f32_e32 v205, v97
	v_mfma_f32_32x32x16_bf16 v[50:65], v[100:103], v[86:89], v[50:65]
	v_mfma_f32_32x32x16_bf16 v[50:65], v[104:107], v[156:159], v[50:65]
	v_mfma_f32_32x32x16_bf16 v[50:65], v[108:111], v[176:179], v[50:65]
	s_add_u32 s28, s61, 0x18182000
	s_mov_b32 m0, s55
	v_lshl_add_u64 v[82:83], v[98:99], 0, s[16:17]
	s_addc_u32 s29, s62, 0
	s_waitcnt vmcnt(0)
	s_waitcnt vmcnt(0)
	s_barrier
	global_load_lds_dwordx4 v[82:83], off
	v_lshl_add_u64 v[82:83], s[28:29], 0, v[152:153]
	s_mov_b32 m0, s34
	v_lshl_add_u64 v[90:91], s[0:1], 0, v[150:151]
	global_load_lds_dwordx4 v[82:83], off
	v_lshl_add_u64 v[82:83], s[28:29], 0, v[154:155]
	s_mov_b32 m0, s54
	v_lshl_add_u64 v[160:161], v[90:91], 0, s[14:15]
	global_load_lds_dwordx4 v[82:83], off
	ds_read_b128 v[82:85], v172 offset:32768
	ds_read_b128 v[86:89], v172 offset:36864
	ds_read_b128 v[156:159], v173 offset:32768
	ds_read_b128 v[176:179], v173 offset:36864
	ds_read_b128 v[180:183], v174 offset:32768
	ds_read_b128 v[184:187], v174 offset:36864
	ds_read_b128 v[188:191], v175 offset:32768
	ds_read_b128 v[192:195], v175 offset:36864
	s_waitcnt lgkmcnt(0)
	v_mfma_f32_32x32x16_bf16 v[98:113], v[82:85], v[114:117], 0
	v_exp_f32_e32 v206, v66
	v_exp_f32_e32 v207, v67
	v_exp_f32_e32 v208, v68
	v_exp_f32_e32 v209, v69
	v_exp_f32_e32 v210, v70
	v_exp_f32_e32 v211, v71
	v_exp_f32_e32 v212, v72
	v_exp_f32_e32 v213, v73
	v_mfma_f32_32x32x16_bf16 v[82:97], v[86:89], v[114:117], 0
	v_exp_f32_e32 v81, v81
	v_mfma_f32_32x32x16_bf16 v[98:113], v[156:159], v[118:121], v[98:113]
	v_exp_f32_e32 v157, v74
	v_exp_f32_e32 v159, v75
	v_exp_f32_e32 v214, v76
	v_exp_f32_e32 v215, v77
	v_exp_f32_e32 v216, v78
	v_exp_f32_e32 v217, v79
	v_exp_f32_e32 v218, v80
	v_mfma_f32_32x32x16_bf16 v[82:97], v[176:179], v[118:121], v[82:97]
	v_add_f32_e32 v66, v139, v141
	v_add_f32_e32 v67, v206, v207
	v_cvt_pk_bf16_f32 v68, v147, v149
	v_add_f32_e32 v66, v66, v143
	v_add_f32_e32 v67, v67, v208
	v_cvt_pk_bf16_f32 v69, v196, v197
	v_add_f32_e32 v66, v66, v145
	v_add_f32_e32 v67, v67, v209
	v_mfma_f32_32x32x16_bf16 v[98:113], v[180:183], v[122:125], v[98:113]
	v_add_f32_e32 v66, v66, v147
	v_add_f32_e32 v67, v67, v210
	s_nop 0
	v_add_f32_e32 v66, v66, v149
	v_add_f32_e32 v67, v67, v211
	s_nop 0
	v_add_f32_e32 v66, v66, v196
	v_add_f32_e32 v67, v67, v212
	v_mfma_f32_32x32x16_bf16 v[82:97], v[184:187], v[122:125], v[82:97]
	v_add_f32_e32 v66, v66, v197
	v_add_f32_e32 v67, v67, v213
	s_nop 0
	v_add_f32_e32 v66, v66, v198
	v_add_f32_e32 v67, v67, v157
	s_nop 0
	v_add_f32_e32 v66, v66, v199
	v_add_f32_e32 v67, v67, v159
	s_nop 0
	v_add_f32_e32 v66, v66, v200
	v_add_f32_e32 v67, v67, v214
	s_nop 0
	v_add_f32_e32 v66, v66, v201
	v_add_f32_e32 v67, v67, v215
	s_nop 0
	v_add_f32_e32 v66, v66, v202
	v_add_f32_e32 v67, v67, v216
	s_nop 0
	v_add_f32_e32 v66, v66, v203
	v_add_f32_e32 v67, v67, v217
	s_nop 0
	v_add_f32_e32 v66, v66, v204
	v_add_f32_e32 v67, v67, v218
	s_nop 0
	v_add_f32_e32 v66, v66, v205
	v_add_f32_e32 v67, v67, v81
	s_nop 0
	v_add_f32_e32 v156, v66, v67
	v_cvt_pk_bf16_f32 v66, v139, v141
	v_cvt_pk_bf16_f32 v67, v143, v145
	v_mov_b32_e32 v158, v156
	v_permlane32_swap_b32_e32 v156, v158
	v_cvt_pk_bf16_f32 v70, v198, v199
	v_cvt_pk_bf16_f32 v71, v200, v201
	v_cvt_pk_bf16_f32 v72, v202, v203
	v_cvt_pk_bf16_f32 v73, v204, v205
	v_cvt_pk_bf16_f32 v74, v206, v207
	v_cvt_pk_bf16_f32 v75, v208, v209
	v_cvt_pk_bf16_f32 v76, v210, v211
	v_cvt_pk_bf16_f32 v77, v212, v213
	v_cvt_pk_bf16_f32 v78, v157, v159
	v_cvt_pk_bf16_f32 v79, v214, v215
	v_cvt_pk_bf16_f32 v80, v216, v217
	v_cvt_pk_bf16_f32 v81, v218, v81
	v_mfma_f32_32x32x16_bf16 v[98:113], v[188:191], v[126:129], v[98:113]
	v_mfma_f32_32x32x16_bf16 v[82:97], v[192:195], v[126:129], v[82:97]
	ds_read_b64_tr_b16 v[176:177], v169 offset:0
	ds_read_b64_tr_b16 v[178:179], v169 offset:0x800
	ds_read_b64_tr_b16 v[180:181], v169 offset:0x1000
	ds_read_b64_tr_b16 v[182:183], v169 offset:0x1800
	ds_read_b64_tr_b16 v[184:185], v169 offset:0x2000
	ds_read_b64_tr_b16 v[186:187], v169 offset:0x2800
	ds_read_b64_tr_b16 v[188:189], v169 offset:0x3000
	ds_read_b64_tr_b16 v[190:191], v169 offset:0x3800
	ds_read_b64_tr_b16 v[192:193], v169 offset:0x200
	ds_read_b64_tr_b16 v[194:195], v169 offset:0xa00
	ds_read_b64_tr_b16 v[196:197], v169 offset:0x1200
	ds_read_b64_tr_b16 v[198:199], v169 offset:0x1a00
	ds_read_b64_tr_b16 v[200:201], v169 offset:0x2200
	ds_read_b64_tr_b16 v[202:203], v169 offset:0x2a00
	ds_read_b64_tr_b16 v[204:205], v169 offset:0x3200
	ds_read_b64_tr_b16 v[206:207], v169 offset:0x3a00
	s_waitcnt lgkmcnt(8)
	s_nop 0
	v_mfma_f32_32x32x16_bf16 v[2:17], v[66:69], v[176:179], v[2:17]
	s_nop 8
	v_exp_f32_e32 v139, v98
	v_exp_f32_e32 v141, v99
	v_exp_f32_e32 v143, v100
	v_exp_f32_e32 v145, v101
	v_mfma_f32_32x32x16_bf16 v[2:17], v[70:73], v[180:183], v[2:17]
	v_mfma_f32_32x32x16_bf16 v[2:17], v[74:77], v[184:187], v[2:17]
	v_mfma_f32_32x32x16_bf16 v[2:17], v[78:81], v[188:191], v[2:17]
	ds_read_b64_tr_b16 v[98:99], v169 offset:0x400
	ds_read_b64_tr_b16 v[100:101], v169 offset:0xc00
	ds_read_b64_tr_b16 v[176:177], v169 offset:0x1400
	ds_read_b64_tr_b16 v[178:179], v169 offset:0x1c00
	ds_read_b64_tr_b16 v[180:181], v169 offset:0x2400
	ds_read_b64_tr_b16 v[182:183], v169 offset:0x2c00
	ds_read_b64_tr_b16 v[184:185], v169 offset:0x3400
	ds_read_b64_tr_b16 v[186:187], v169 offset:0x3c00
	s_waitcnt lgkmcnt(8)
	v_mfma_f32_32x32x16_bf16 v[18:33], v[66:69], v[192:195], v[18:33]
	v_exp_f32_e32 v147, v102
	v_exp_f32_e32 v149, v103
	v_mfma_f32_32x32x16_bf16 v[18:33], v[70:73], v[196:199], v[18:33]
	v_mfma_f32_32x32x16_bf16 v[18:33], v[74:77], v[200:203], v[18:33]
	v_exp_f32_e32 v200, v104
	v_exp_f32_e32 v201, v105
	v_mfma_f32_32x32x16_bf16 v[18:33], v[78:81], v[204:207], v[18:33]
	ds_read_b64_tr_b16 v[102:103], v169 offset:0x600
	ds_read_b64_tr_b16 v[104:105], v169 offset:0xe00
	ds_read_b64_tr_b16 v[188:189], v169 offset:0x1600
	ds_read_b64_tr_b16 v[190:191], v169 offset:0x1e00
	ds_read_b64_tr_b16 v[192:193], v169 offset:0x2600
	ds_read_b64_tr_b16 v[194:195], v169 offset:0x2e00
	ds_read_b64_tr_b16 v[196:197], v169 offset:0x3600
	ds_read_b64_tr_b16 v[198:199], v169 offset:0x3e00
	s_waitcnt lgkmcnt(8)
	v_mfma_f32_32x32x16_bf16 v[34:49], v[66:69], v[98:101], v[34:49]
	v_exp_f32_e32 v202, v106
	v_exp_f32_e32 v203, v107
	v_exp_f32_e32 v204, v108
	v_exp_f32_e32 v205, v109
	v_mfma_f32_32x32x16_bf16 v[34:49], v[70:73], v[176:179], v[34:49]
	v_mfma_f32_32x32x16_bf16 v[34:49], v[74:77], v[180:183], v[34:49]
	v_mfma_f32_32x32x16_bf16 v[34:49], v[78:81], v[184:187], v[34:49]
	s_waitcnt lgkmcnt(0)
	v_mfma_f32_32x32x16_bf16 v[50:65], v[66:69], v[102:105], v[50:65]
	v_exp_f32_e32 v206, v110
	v_exp_f32_e32 v207, v111
	v_exp_f32_e32 v208, v112
	v_exp_f32_e32 v209, v113
	v_mfma_f32_32x32x16_bf16 v[50:65], v[70:73], v[188:191], v[50:65]
	v_mfma_f32_32x32x16_bf16 v[50:65], v[74:77], v[192:195], v[50:65]
	v_mfma_f32_32x32x16_bf16 v[50:65], v[78:81], v[196:199], v[50:65]
	s_add_u32 s0, s61, 0x18242000
	s_mov_b32 m0, s35
	s_addc_u32 s1, s62, 0
	s_waitcnt vmcnt(0)
	s_waitcnt vmcnt(0)
	s_barrier
	global_load_lds_dwordx4 v[160:161], off
	v_lshl_add_u64 v[66:67], s[0:1], 0, v[152:153]
	s_mov_b32 m0, s56
	s_nop 0
	global_load_lds_dwordx4 v[66:67], off
	v_lshl_add_u64 v[66:67], s[0:1], 0, v[154:155]
	s_mov_b32 m0, s57
	s_nop 0
	global_load_lds_dwordx4 v[66:67], off
	ds_read_b128 v[66:69], v172 offset:40960
	ds_read_b128 v[70:73], v172 offset:45056
	ds_read_b128 v[152:155], v173 offset:40960
	ds_read_b128 v[176:179], v173 offset:45056
	ds_read_b128 v[180:183], v174 offset:40960
	ds_read_b128 v[184:187], v174 offset:45056
	ds_read_b128 v[188:191], v175 offset:40960
	ds_read_b128 v[192:195], v175 offset:45056
	s_waitcnt lgkmcnt(0)
	v_mfma_f32_32x32x16_bf16 v[98:113], v[66:69], v[114:117], 0
	v_exp_f32_e32 v160, v82
	v_exp_f32_e32 v161, v83
	v_exp_f32_e32 v196, v84
	v_exp_f32_e32 v197, v85
	v_exp_f32_e32 v198, v86
	v_exp_f32_e32 v199, v87
	v_exp_f32_e32 v210, v88
	v_mfma_f32_32x32x16_bf16 v[66:81], v[70:73], v[114:117], 0
	v_exp_f32_e32 v211, v89
	v_mfma_f32_32x32x16_bf16 v[66:81], v[176:179], v[118:121], v[66:81]
	v_exp_f32_e32 v212, v94
	v_exp_f32_e32 v213, v95
	v_exp_f32_e32 v214, v96
	v_exp_f32_e32 v97, v97
	v_mfma_f32_32x32x16_bf16 v[98:113], v[152:155], v[118:121], v[98:113]
	v_exp_f32_e32 v152, v90
	v_exp_f32_e32 v153, v91
	v_exp_f32_e32 v154, v92
	v_exp_f32_e32 v155, v93
	v_add_f32_e32 v82, v139, v141
	v_add_f32_e32 v83, v160, v161
	v_mfma_f32_32x32x16_bf16 v[66:81], v[184:187], v[122:125], v[66:81]
	v_add_f32_e32 v82, v82, v143
	v_add_f32_e32 v83, v83, v196
	v_cvt_pk_bf16_f32 v84, v147, v149
	v_add_f32_e32 v82, v82, v145
	v_add_f32_e32 v83, v83, v197
	v_cvt_pk_bf16_f32 v85, v200, v201
	v_add_f32_e32 v82, v82, v147
	v_add_f32_e32 v83, v83, v198
	v_mfma_f32_32x32x16_bf16 v[98:113], v[180:183], v[122:125], v[98:113]
	v_add_f32_e32 v82, v82, v149
	v_add_f32_e32 v83, v83, v199
	s_nop 0
	v_add_f32_e32 v82, v82, v200
	v_add_f32_e32 v83, v83, v210
	s_nop 0
	v_add_f32_e32 v82, v82, v201
	v_add_f32_e32 v83, v83, v211
	s_nop 0
	v_add_f32_e32 v82, v82, v202
	v_add_f32_e32 v83, v83, v152
	s_nop 0
	v_add_f32_e32 v82, v82, v203
	v_add_f32_e32 v83, v83, v153
	s_nop 0
	v_add_f32_e32 v82, v82, v204
	v_add_f32_e32 v83, v83, v154
	s_nop 0
	v_add_f32_e32 v82, v82, v205
	v_add_f32_e32 v83, v83, v155
	s_nop 0
	v_add_f32_e32 v82, v82, v206
	v_add_f32_e32 v83, v83, v212
	s_nop 0
	v_add_f32_e32 v82, v82, v207
	v_add_f32_e32 v83, v83, v213
	s_nop 0
	v_add_f32_e32 v82, v82, v208
	v_add_f32_e32 v83, v83, v214
	s_nop 0
	v_add_f32_e32 v82, v82, v209
	v_add_f32_e32 v83, v83, v97
	s_nop 0
	v_add_f32_e32 v157, v82, v83
	v_mov_b32_e32 v159, v157
	s_nop 1
	v_permlane32_swap_b32_e32 v157, v159
	v_add_f32_e64 v82, v156, v158
	v_add_f32_e64 v83, v157, v159
	v_add_f32_e32 v82, v135, v82
	v_add_f32_e32 v135, v82, v83
	v_cvt_pk_bf16_f32 v82, v139, v141
	v_cvt_pk_bf16_f32 v83, v143, v145
	v_mfma_f32_32x32x16_bf16 v[66:81], v[192:195], v[126:129], v[66:81]
	v_cvt_pk_bf16_f32 v86, v202, v203
	v_cvt_pk_bf16_f32 v87, v204, v205
	v_cvt_pk_bf16_f32 v88, v206, v207
	v_cvt_pk_bf16_f32 v89, v208, v209
	v_cvt_pk_bf16_f32 v90, v160, v161
	v_cvt_pk_bf16_f32 v91, v196, v197
	v_cvt_pk_bf16_f32 v92, v198, v199
	v_cvt_pk_bf16_f32 v93, v210, v211
	v_cvt_pk_bf16_f32 v94, v152, v153
	v_cvt_pk_bf16_f32 v95, v154, v155
	v_cvt_pk_bf16_f32 v96, v212, v213
	v_cvt_pk_bf16_f32 v97, v214, v97
	v_mfma_f32_32x32x16_bf16 v[98:113], v[188:191], v[126:129], v[98:113]
	ds_read_b64_tr_b16 v[152:153], v168 offset:0
	ds_read_b64_tr_b16 v[154:155], v168 offset:0x800
	ds_read_b64_tr_b16 v[156:157], v168 offset:0x1000
	ds_read_b64_tr_b16 v[158:159], v168 offset:0x1800
	ds_read_b64_tr_b16 v[176:177], v168 offset:0x2000
	ds_read_b64_tr_b16 v[178:179], v168 offset:0x2800
	ds_read_b64_tr_b16 v[180:181], v168 offset:0x3000
	ds_read_b64_tr_b16 v[182:183], v168 offset:0x3800
	ds_read_b64_tr_b16 v[184:185], v168 offset:0x200
	ds_read_b64_tr_b16 v[186:187], v168 offset:0xa00
	ds_read_b64_tr_b16 v[188:189], v168 offset:0x1200
	ds_read_b64_tr_b16 v[190:191], v168 offset:0x1a00
	ds_read_b64_tr_b16 v[192:193], v168 offset:0x2200
	ds_read_b64_tr_b16 v[194:195], v168 offset:0x2a00
	ds_read_b64_tr_b16 v[196:197], v168 offset:0x3200
	ds_read_b64_tr_b16 v[198:199], v168 offset:0x3a00
	s_waitcnt lgkmcnt(8)
	s_nop 0
	v_mfma_f32_32x32x16_bf16 v[2:17], v[82:85], v[152:155], v[2:17]
	s_nop 3
	v_exp_f32_e32 v139, v98
	v_exp_f32_e32 v141, v99
	v_exp_f32_e32 v143, v100
	v_exp_f32_e32 v145, v101
	v_mfma_f32_32x32x16_bf16 v[2:17], v[86:89], v[156:159], v[2:17]
	v_mfma_f32_32x32x16_bf16 v[2:17], v[90:93], v[176:179], v[2:17]
	v_mfma_f32_32x32x16_bf16 v[2:17], v[94:97], v[180:183], v[2:17]
	ds_read_b64_tr_b16 v[98:99], v168 offset:0x400
	ds_read_b64_tr_b16 v[100:101], v168 offset:0xc00
	ds_read_b64_tr_b16 v[152:153], v168 offset:0x1400
	ds_read_b64_tr_b16 v[154:155], v168 offset:0x1c00
	ds_read_b64_tr_b16 v[156:157], v168 offset:0x2400
	ds_read_b64_tr_b16 v[158:159], v168 offset:0x2c00
	ds_read_b64_tr_b16 v[200:201], v168 offset:0x3400
	ds_read_b64_tr_b16 v[202:203], v168 offset:0x3c00
	s_waitcnt lgkmcnt(8)
	v_mfma_f32_32x32x16_bf16 v[18:33], v[82:85], v[184:187], v[18:33]
	v_exp_f32_e32 v147, v102
	v_exp_f32_e32 v149, v103
	v_exp_f32_e32 v176, v104
	v_exp_f32_e32 v177, v105
	v_mfma_f32_32x32x16_bf16 v[18:33], v[86:89], v[188:191], v[18:33]
	v_mfma_f32_32x32x16_bf16 v[18:33], v[90:93], v[192:195], v[18:33]
	v_mfma_f32_32x32x16_bf16 v[18:33], v[94:97], v[196:199], v[18:33]
	ds_read_b64_tr_b16 v[102:103], v168 offset:0x600
	ds_read_b64_tr_b16 v[104:105], v168 offset:0xe00
	ds_read_b64_tr_b16 v[182:183], v168 offset:0x1600
	ds_read_b64_tr_b16 v[184:185], v168 offset:0x1e00
	ds_read_b64_tr_b16 v[186:187], v168 offset:0x2600
	ds_read_b64_tr_b16 v[188:189], v168 offset:0x2e00
	ds_read_b64_tr_b16 v[190:191], v168 offset:0x3600
	ds_read_b64_tr_b16 v[192:193], v168 offset:0x3e00
	s_waitcnt lgkmcnt(8)
	v_mfma_f32_32x32x16_bf16 v[34:49], v[82:85], v[98:101], v[34:49]
	v_exp_f32_e32 v178, v106
	v_exp_f32_e32 v179, v107
	v_exp_f32_e32 v180, v108
	v_exp_f32_e32 v181, v109
	v_mfma_f32_32x32x16_bf16 v[34:49], v[86:89], v[152:155], v[34:49]
	v_mfma_f32_32x32x16_bf16 v[34:49], v[90:93], v[156:159], v[34:49]
	v_mfma_f32_32x32x16_bf16 v[34:49], v[94:97], v[200:203], v[34:49]
	s_waitcnt lgkmcnt(0)
	v_mfma_f32_32x32x16_bf16 v[50:65], v[82:85], v[102:105], v[50:65]
	v_mfma_f32_32x32x16_bf16 v[50:65], v[86:89], v[182:185], v[50:65]
	v_exp_f32_e32 v182, v110
	v_exp_f32_e32 v183, v111
	v_exp_f32_e32 v184, v112
	v_exp_f32_e32 v185, v113
	v_mfma_f32_32x32x16_bf16 v[50:65], v[90:93], v[186:189], v[50:65]
	v_mfma_f32_32x32x16_bf16 v[50:65], v[94:97], v[190:193], v[50:65]
	v_add_u32_e32 v82, s60, v163
	v_lshrrev_b32_e32 v83, 1, v82
	v_xor_b32_e32 v83, v83, v82
	v_and_b32_e32 v83, 4, v83
	v_lshl_or_b32 v83, v83, 1, v83
	v_xor_b32_e32 v82, v82, v83
	v_mul_lo_u32 v82, v82, s22
	v_or3_b32 v82, v162, v82, v137
	v_ashrrev_i32_e32 v83, 31, v82
	v_lshlrev_b64 v[152:153], 1, v[82:83]
	v_add_u32_e32 v82, s59, v163
	v_lshrrev_b32_e32 v83, 1, v82
	v_xor_b32_e32 v83, v83, v82
	v_and_b32_e32 v83, 4, v83
	v_lshl_or_b32 v83, v83, 1, v83
	v_xor_b32_e32 v82, v82, v83
	v_mul_lo_u32 v82, v82, s22
	v_or3_b32 v82, v162, v82, v137
	s_waitcnt vmcnt(0)
	v_ashrrev_i32_e32 v83, 31, v82
	s_add_u32 s0, s90, s58
	v_lshlrev_b64 v[154:155], 1, v[82:83]
	v_lshl_add_u64 v[150:151], s[52:53], 0, v[150:151]
	s_addc_u32 s1, s91, s25
	v_or_b32_e32 v152, s24, v152
	v_or_b32_e32 v154, s24, v154
	s_mov_b32 s52, 4
	s_waitcnt vmcnt(0)
	s_barrier
	v_exp_f32_e32 v220, v66
	v_exp_f32_e32 v221, v67
	v_exp_f32_e32 v222, v68
	v_exp_f32_e32 v223, v69
	v_exp_f32_e32 v224, v70
	v_exp_f32_e32 v225, v71
	v_exp_f32_e32 v226, v72
	v_exp_f32_e32 v227, v73
	v_exp_f32_e32 v228, v74
	v_exp_f32_e32 v229, v75
	v_exp_f32_e32 v230, v76
	v_exp_f32_e32 v231, v77
	v_exp_f32_e32 v232, v78
	v_exp_f32_e32 v233, v79
	v_exp_f32_e32 v234, v80
	v_exp_f32_e32 v235, v81
	s_branch .LBB0_2320
.LBB0_2319:
	s_mov_b32 m0, s56
	v_lshl_add_u64 v[68:69], v[156:157], 0, s[44:45]
	global_load_lds_dwordx4 v[68:69], off
	v_lshl_add_u64 v[68:69], v[158:159], 0, s[44:45]
	s_mov_b32 m0, s57
	global_load_lds_dwordx4 v[68:69], off
	ds_read_b128 v[68:71], v172 offset:40960
	ds_read_b128 v[72:75], v172 offset:45056
	ds_read_b128 v[156:159], v173 offset:40960
	ds_read_b128 v[176:179], v173 offset:45056
	ds_read_b128 v[180:183], v174 offset:40960
	ds_read_b128 v[184:187], v174 offset:45056
	ds_read_b128 v[188:191], v175 offset:40960
	ds_read_b128 v[192:195], v175 offset:45056
	v_add_f32_e32 v219, v219, v66
	s_add_i32 s52, s52, 2
	s_waitcnt lgkmcnt(0)
	v_mfma_f32_32x32x16_bf16 v[98:113], v[68:71], v[114:117], 0
	v_mfma_f32_32x32x16_bf16 v[66:81], v[72:75], v[114:117], 0
	v_mfma_f32_32x32x16_bf16 v[66:81], v[176:179], v[118:121], v[66:81]
	v_mfma_f32_32x32x16_bf16 v[98:113], v[156:159], v[118:121], v[98:113]
	v_add_f32_e32 v82, v236, v237
	v_add_f32_e32 v83, v220, v221
	v_mfma_f32_32x32x16_bf16 v[66:81], v[184:187], v[122:125], v[66:81]
	v_add_f32_e32 v82, v82, v238
	v_add_f32_e32 v83, v83, v222
	v_cvt_pk_bf16_f32 v84, v240, v241
	v_add_f32_e32 v82, v82, v239
	v_add_f32_e32 v83, v83, v223
	v_cvt_pk_bf16_f32 v85, v244, v245
	v_add_f32_e32 v82, v82, v240
	v_add_f32_e32 v83, v83, v224
	v_mfma_f32_32x32x16_bf16 v[98:113], v[180:183], v[122:125], v[98:113]
	v_add_f32_e32 v82, v82, v241
	v_add_f32_e32 v83, v83, v225
	v_add_f32_e32 v82, v82, v244
	v_add_f32_e32 v83, v83, v226
	v_add_f32_e32 v82, v82, v245
	v_add_f32_e32 v83, v83, v227
	v_add_f32_e32 v82, v82, v246
	v_add_f32_e32 v83, v83, v228
	v_add_f32_e32 v82, v82, v247
	v_add_f32_e32 v83, v83, v229
	v_add_f32_e32 v82, v82, v248
	v_add_f32_e32 v83, v83, v230
	v_add_f32_e32 v82, v82, v249
	v_add_f32_e32 v83, v83, v231
	v_add_f32_e32 v82, v82, v250
	v_add_f32_e32 v83, v83, v232
	v_add_f32_e32 v82, v82, v251
	v_add_f32_e32 v83, v83, v233
	v_add_f32_e32 v82, v82, v252
	v_add_f32_e32 v83, v83, v234
	v_add_f32_e32 v82, v82, v253
	v_add_f32_e32 v83, v83, v235
	v_add_f32_e32 v82, v82, v83
	v_add_f32_e32 v219, v219, v82
	v_cvt_pk_bf16_f32 v82, v236, v237
	v_cvt_pk_bf16_f32 v83, v238, v239
	v_mfma_f32_32x32x16_bf16 v[66:81], v[192:195], v[126:129], v[66:81]
	v_cvt_pk_bf16_f32 v86, v246, v247
	v_cvt_pk_bf16_f32 v87, v248, v249
	v_cvt_pk_bf16_f32 v88, v250, v251
	v_cvt_pk_bf16_f32 v89, v252, v253
	v_cvt_pk_bf16_f32 v90, v220, v221
	v_cvt_pk_bf16_f32 v91, v222, v223
	v_cvt_pk_bf16_f32 v92, v224, v225
	v_cvt_pk_bf16_f32 v93, v226, v227
	v_cvt_pk_bf16_f32 v94, v228, v229
	v_cvt_pk_bf16_f32 v95, v230, v231
	v_cvt_pk_bf16_f32 v96, v232, v233
	v_cvt_pk_bf16_f32 v97, v234, v235
	v_mfma_f32_32x32x16_bf16 v[98:113], v[188:191], v[126:129], v[98:113]
	ds_read_b64_tr_b16 v[156:157], v168 offset:0
	ds_read_b64_tr_b16 v[158:159], v168 offset:0x800
	ds_read_b64_tr_b16 v[176:177], v168 offset:0x1000
	ds_read_b64_tr_b16 v[178:179], v168 offset:0x1800
	ds_read_b64_tr_b16 v[180:181], v168 offset:0x2000
	ds_read_b64_tr_b16 v[182:183], v168 offset:0x2800
	ds_read_b64_tr_b16 v[184:185], v168 offset:0x3000
	ds_read_b64_tr_b16 v[186:187], v168 offset:0x3800
	ds_read_b64_tr_b16 v[188:189], v168 offset:0x200
	ds_read_b64_tr_b16 v[190:191], v168 offset:0xa00
	ds_read_b64_tr_b16 v[192:193], v168 offset:0x1200
	ds_read_b64_tr_b16 v[194:195], v168 offset:0x1a00
	ds_read_b64_tr_b16 v[196:197], v168 offset:0x2200
	ds_read_b64_tr_b16 v[198:199], v168 offset:0x2a00
	ds_read_b64_tr_b16 v[200:201], v168 offset:0x3200
	ds_read_b64_tr_b16 v[202:203], v168 offset:0x3a00
	s_waitcnt lgkmcnt(8)
	s_nop 0
	v_mfma_f32_32x32x16_bf16 v[2:17], v[82:85], v[156:159], v[2:17]
	v_exp_f32_e32 v220, v66
	s_nop 3
	v_exp_f32_e32 v139, v98
	v_exp_f32_e32 v141, v99
	v_exp_f32_e32 v143, v100
	v_exp_f32_e32 v145, v101
	v_mfma_f32_32x32x16_bf16 v[2:17], v[86:89], v[176:179], v[2:17]
	v_exp_f32_e32 v221, v67
	v_mfma_f32_32x32x16_bf16 v[2:17], v[90:93], v[180:183], v[2:17]
	v_exp_f32_e32 v222, v68
	v_mfma_f32_32x32x16_bf16 v[2:17], v[94:97], v[184:187], v[2:17]
	v_exp_f32_e32 v223, v69
	ds_read_b64_tr_b16 v[98:99], v168 offset:0x400
	ds_read_b64_tr_b16 v[100:101], v168 offset:0xc00
	ds_read_b64_tr_b16 v[156:157], v168 offset:0x1400
	ds_read_b64_tr_b16 v[158:159], v168 offset:0x1c00
	ds_read_b64_tr_b16 v[178:179], v168 offset:0x2400
	ds_read_b64_tr_b16 v[180:181], v168 offset:0x2c00
	ds_read_b64_tr_b16 v[182:183], v168 offset:0x3400
	ds_read_b64_tr_b16 v[184:185], v168 offset:0x3c00
	s_waitcnt lgkmcnt(8)
	v_mfma_f32_32x32x16_bf16 v[18:33], v[82:85], v[188:191], v[18:33]
	v_exp_f32_e32 v224, v70
	v_exp_f32_e32 v147, v102
	v_exp_f32_e32 v149, v103
	v_exp_f32_e32 v176, v104
	v_exp_f32_e32 v177, v105
	v_mfma_f32_32x32x16_bf16 v[18:33], v[86:89], v[192:195], v[18:33]
	v_exp_f32_e32 v225, v71
	v_mfma_f32_32x32x16_bf16 v[18:33], v[90:93], v[196:199], v[18:33]
	v_exp_f32_e32 v226, v72
	v_mfma_f32_32x32x16_bf16 v[18:33], v[94:97], v[200:203], v[18:33]
	v_exp_f32_e32 v227, v73
	ds_read_b64_tr_b16 v[102:103], v168 offset:0x600
	ds_read_b64_tr_b16 v[104:105], v168 offset:0xe00
	ds_read_b64_tr_b16 v[186:187], v168 offset:0x1600
	ds_read_b64_tr_b16 v[188:189], v168 offset:0x1e00
	ds_read_b64_tr_b16 v[190:191], v168 offset:0x2600
	ds_read_b64_tr_b16 v[192:193], v168 offset:0x2e00
	ds_read_b64_tr_b16 v[194:195], v168 offset:0x3600
	ds_read_b64_tr_b16 v[196:197], v168 offset:0x3e00
	s_waitcnt lgkmcnt(8)
	v_mfma_f32_32x32x16_bf16 v[34:49], v[82:85], v[98:101], v[34:49]
	v_exp_f32_e32 v228, v74
	v_mfma_f32_32x32x16_bf16 v[34:49], v[86:89], v[156:159], v[34:49]
	v_exp_f32_e32 v229, v75
	v_mfma_f32_32x32x16_bf16 v[34:49], v[90:93], v[178:181], v[34:49]
	v_exp_f32_e32 v230, v76
	v_exp_f32_e32 v178, v106
	v_exp_f32_e32 v179, v107
	v_exp_f32_e32 v180, v108
	v_exp_f32_e32 v181, v109
	v_mfma_f32_32x32x16_bf16 v[34:49], v[94:97], v[182:185], v[34:49]
	v_exp_f32_e32 v231, v77
	s_waitcnt lgkmcnt(0)
	v_mfma_f32_32x32x16_bf16 v[50:65], v[82:85], v[102:105], v[50:65]
	v_exp_f32_e32 v232, v78
	v_exp_f32_e32 v182, v110
	v_exp_f32_e32 v183, v111
	v_exp_f32_e32 v184, v112
	v_exp_f32_e32 v185, v113
	v_mfma_f32_32x32x16_bf16 v[50:65], v[86:89], v[186:189], v[50:65]
	v_exp_f32_e32 v233, v79
	v_mfma_f32_32x32x16_bf16 v[50:65], v[90:93], v[190:193], v[50:65]
	v_exp_f32_e32 v234, v80
	v_mfma_f32_32x32x16_bf16 v[50:65], v[94:97], v[194:197], v[50:65]
	v_exp_f32_e32 v235, v81
	s_waitcnt vmcnt(0)
	s_add_u32 s0, s0, 0x180000
	s_addc_u32 s1, s1, 0
	s_and_b64 vcc, exec, s[24:25]
	s_waitcnt vmcnt(0)
	s_barrier
	s_cbranch_vccnz .LBB0_2322
.LBB0_2320:
	v_lshl_add_u64 v[160:161], s[0:1], 0, v[150:151]
	s_mov_b32 m0, s55
	v_lshl_add_u64 v[82:83], v[160:161], 0, s[18:19]
	v_lshl_add_u64 v[156:157], s[0:1], 0, v[152:153]
	global_load_lds_dwordx4 v[82:83], off
	v_lshl_add_u64 v[82:83], v[156:157], 0, s[36:37]
	s_mov_b32 m0, s34
	v_lshl_add_u64 v[158:159], s[0:1], 0, v[154:155]
	global_load_lds_dwordx4 v[82:83], off
	v_lshl_add_u64 v[82:83], v[158:159], 0, s[36:37]
	s_mov_b32 m0, s54
	s_nop 0
	global_load_lds_dwordx4 v[82:83], off
	ds_read_b128 v[82:85], v172 offset:32768
	ds_read_b128 v[86:89], v172 offset:36864
	ds_read_b128 v[186:189], v173 offset:32768
	ds_read_b128 v[190:193], v173 offset:36864
	ds_read_b128 v[194:197], v174 offset:32768
	ds_read_b128 v[198:201], v174 offset:36864
	ds_read_b128 v[202:205], v175 offset:32768
	ds_read_b128 v[206:209], v175 offset:36864
	s_waitcnt lgkmcnt(0)
	v_mfma_f32_32x32x16_bf16 v[98:113], v[82:85], v[114:117], 0
	v_mfma_f32_32x32x16_bf16 v[82:97], v[86:89], v[114:117], 0
	v_mfma_f32_32x32x16_bf16 v[98:113], v[186:189], v[118:121], v[98:113]
	v_mfma_f32_32x32x16_bf16 v[82:97], v[190:193], v[118:121], v[82:97]
	v_add_f32_e32 v66, v139, v141
	v_add_f32_e32 v67, v220, v221
	v_mfma_f32_32x32x16_bf16 v[98:113], v[194:197], v[122:125], v[98:113]
	v_add_f32_e32 v66, v66, v143
	v_add_f32_e32 v67, v67, v222
	v_cvt_pk_bf16_f32 v68, v139, v141
	v_add_f32_e32 v66, v66, v145
	v_add_f32_e32 v67, v67, v223
	v_cvt_pk_bf16_f32 v69, v143, v145
	v_add_f32_e32 v66, v66, v147
	v_add_f32_e32 v67, v67, v224
	v_mfma_f32_32x32x16_bf16 v[82:97], v[198:201], v[122:125], v[82:97]
	v_add_f32_e32 v66, v66, v149
	v_add_f32_e32 v67, v67, v225
	v_cvt_pk_bf16_f32 v70, v147, v149
	v_add_f32_e32 v66, v66, v176
	v_add_f32_e32 v67, v67, v226
	v_cvt_pk_bf16_f32 v71, v176, v177
	v_add_f32_e32 v66, v66, v177
	v_add_f32_e32 v67, v67, v227
	s_nop 0
	v_add_f32_e32 v66, v66, v178
	v_add_f32_e32 v67, v67, v228
	v_add_f32_e32 v66, v66, v179
	v_add_f32_e32 v67, v67, v229
	v_add_f32_e32 v66, v66, v180
	v_add_f32_e32 v67, v67, v230
	v_add_f32_e32 v66, v66, v181
	v_add_f32_e32 v67, v67, v231
	v_add_f32_e32 v66, v66, v182
	v_add_f32_e32 v67, v67, v232
	v_add_f32_e32 v66, v66, v183
	v_add_f32_e32 v67, v67, v233
	v_add_f32_e32 v66, v66, v184
	v_add_f32_e32 v67, v67, v234
	v_add_f32_e32 v66, v66, v185
	v_add_f32_e32 v67, v67, v235
	v_add_f32_e32 v66, v66, v67
	v_mfma_f32_32x32x16_bf16 v[98:113], v[202:205], v[126:129], v[98:113]
	v_cvt_pk_bf16_f32 v72, v178, v179
	v_cvt_pk_bf16_f32 v73, v180, v181
	v_cvt_pk_bf16_f32 v74, v182, v183
	v_cvt_pk_bf16_f32 v75, v184, v185
	v_cvt_pk_bf16_f32 v76, v220, v221
	v_cvt_pk_bf16_f32 v77, v222, v223
	v_cvt_pk_bf16_f32 v78, v224, v225
	v_mfma_f32_32x32x16_bf16 v[82:97], v[206:209], v[126:129], v[82:97]
	v_cvt_pk_bf16_f32 v79, v226, v227
	v_cvt_pk_bf16_f32 v176, v228, v229
	v_cvt_pk_bf16_f32 v177, v230, v231
	v_cvt_pk_bf16_f32 v178, v232, v233
	v_cvt_pk_bf16_f32 v179, v234, v235
	ds_read_b64_tr_b16 v[180:181], v169 offset:0
	ds_read_b64_tr_b16 v[182:183], v169 offset:0x800
	ds_read_b64_tr_b16 v[184:185], v169 offset:0x1000
	ds_read_b64_tr_b16 v[186:187], v169 offset:0x1800
	ds_read_b64_tr_b16 v[188:189], v169 offset:0x2000
	ds_read_b64_tr_b16 v[190:191], v169 offset:0x2800
	ds_read_b64_tr_b16 v[192:193], v169 offset:0x3000
	ds_read_b64_tr_b16 v[194:195], v169 offset:0x3800
	ds_read_b64_tr_b16 v[196:197], v169 offset:0x200
	ds_read_b64_tr_b16 v[198:199], v169 offset:0xa00
	ds_read_b64_tr_b16 v[200:201], v169 offset:0x1200
	ds_read_b64_tr_b16 v[202:203], v169 offset:0x1a00
	ds_read_b64_tr_b16 v[204:205], v169 offset:0x2200
	ds_read_b64_tr_b16 v[206:207], v169 offset:0x2a00
	ds_read_b64_tr_b16 v[208:209], v169 offset:0x3200
	ds_read_b64_tr_b16 v[210:211], v169 offset:0x3a00
	s_waitcnt lgkmcnt(8)
	s_nop 0
	v_mfma_f32_32x32x16_bf16 v[2:17], v[68:71], v[180:183], v[2:17]
	v_exp_f32_e32 v236, v98
	v_exp_f32_e32 v237, v99
	v_mfma_f32_32x32x16_bf16 v[2:17], v[72:75], v[184:187], v[2:17]
	v_exp_f32_e32 v238, v100
	v_exp_f32_e32 v239, v101
	v_mfma_f32_32x32x16_bf16 v[2:17], v[76:79], v[188:191], v[2:17]
	v_exp_f32_e32 v240, v102
	v_exp_f32_e32 v241, v103
	v_mfma_f32_32x32x16_bf16 v[2:17], v[176:179], v[192:195], v[2:17]
	v_exp_f32_e32 v244, v104
	v_exp_f32_e32 v245, v105
	ds_read_b64_tr_b16 v[180:181], v169 offset:0x400
	ds_read_b64_tr_b16 v[182:183], v169 offset:0xc00
	ds_read_b64_tr_b16 v[184:185], v169 offset:0x1400
	ds_read_b64_tr_b16 v[186:187], v169 offset:0x1c00
	ds_read_b64_tr_b16 v[188:189], v169 offset:0x2400
	ds_read_b64_tr_b16 v[190:191], v169 offset:0x2c00
	ds_read_b64_tr_b16 v[192:193], v169 offset:0x3400
	ds_read_b64_tr_b16 v[194:195], v169 offset:0x3c00
	s_waitcnt lgkmcnt(8)
	v_mfma_f32_32x32x16_bf16 v[18:33], v[68:71], v[196:199], v[18:33]
	v_exp_f32_e32 v246, v106
	v_exp_f32_e32 v247, v107
	v_mfma_f32_32x32x16_bf16 v[18:33], v[72:75], v[200:203], v[18:33]
	v_exp_f32_e32 v248, v108
	v_exp_f32_e32 v249, v109
	v_mfma_f32_32x32x16_bf16 v[18:33], v[76:79], v[204:207], v[18:33]
	v_exp_f32_e32 v250, v110
	v_exp_f32_e32 v251, v111
	v_mfma_f32_32x32x16_bf16 v[18:33], v[176:179], v[208:211], v[18:33]
	v_exp_f32_e32 v252, v112
	v_exp_f32_e32 v253, v113
	ds_read_b64_tr_b16 v[196:197], v169 offset:0x600
	ds_read_b64_tr_b16 v[198:199], v169 offset:0xe00
	ds_read_b64_tr_b16 v[200:201], v169 offset:0x1600
	ds_read_b64_tr_b16 v[202:203], v169 offset:0x1e00
	ds_read_b64_tr_b16 v[204:205], v169 offset:0x2600
	ds_read_b64_tr_b16 v[206:207], v169 offset:0x2e00
	ds_read_b64_tr_b16 v[208:209], v169 offset:0x3600
	ds_read_b64_tr_b16 v[210:211], v169 offset:0x3e00
	s_waitcnt lgkmcnt(8)
	v_mfma_f32_32x32x16_bf16 v[34:49], v[68:71], v[180:183], v[34:49]
	v_exp_f32_e32 v220, v82
	v_exp_f32_e32 v221, v83
	v_mfma_f32_32x32x16_bf16 v[34:49], v[72:75], v[184:187], v[34:49]
	v_exp_f32_e32 v222, v84
	v_exp_f32_e32 v223, v85
	v_mfma_f32_32x32x16_bf16 v[34:49], v[76:79], v[188:191], v[34:49]
	v_exp_f32_e32 v224, v86
	v_exp_f32_e32 v225, v87
	v_mfma_f32_32x32x16_bf16 v[34:49], v[176:179], v[192:195], v[34:49]
	v_exp_f32_e32 v226, v88
	v_exp_f32_e32 v227, v89
	s_waitcnt lgkmcnt(0)
	v_mfma_f32_32x32x16_bf16 v[50:65], v[68:71], v[196:199], v[50:65]
	v_exp_f32_e32 v228, v90
	v_exp_f32_e32 v229, v91
	v_mfma_f32_32x32x16_bf16 v[50:65], v[72:75], v[200:203], v[50:65]
	v_exp_f32_e32 v230, v92
	v_exp_f32_e32 v231, v93
	v_mfma_f32_32x32x16_bf16 v[50:65], v[76:79], v[204:207], v[50:65]
	v_exp_f32_e32 v232, v94
	v_exp_f32_e32 v233, v95
	v_mfma_f32_32x32x16_bf16 v[50:65], v[176:179], v[208:211], v[50:65]
	v_exp_f32_e32 v234, v96
	v_exp_f32_e32 v235, v97
	s_waitcnt vmcnt(0)
	s_cmpk_gt_u32 s52, 0x101
	s_cselect_b64 s[24:25], -1, 0
	s_and_b64 vcc, exec, s[24:25]
	s_waitcnt vmcnt(0)
	s_barrier
	s_cbranch_vccnz .LBB0_2319
	v_lshl_add_u64 v[68:69], v[160:161], 0, s[38:39]
	s_mov_b32 m0, s35
	s_nop 0
	global_load_lds_dwordx4 v[68:69], off
	s_branch .LBB0_2319
.LBB0_2322:
	v_exp_f32_e32 v82, v66
	v_add_f32_e32 v66, 0, v139
	v_add_f32_e32 v66, v141, v66
	v_add_f32_e32 v66, v143, v66
	v_add_f32_e32 v66, v145, v66
	v_add_f32_e32 v66, v147, v66
	v_add_f32_e32 v66, v149, v66
	v_add_f32_e32 v66, v176, v66
	v_add_f32_e32 v66, v177, v66
	v_add_f32_e32 v66, v178, v66
	v_add_f32_e32 v66, v179, v66
	v_add_f32_e32 v66, v180, v66
	v_add_f32_e32 v66, v181, v66
	v_add_f32_e32 v66, v182, v66
	v_exp_f32_e32 v83, v67
	v_add_f32_e32 v66, v183, v66
	v_exp_f32_e32 v84, v68
	v_add_f32_e32 v66, v184, v66
	v_exp_f32_e32 v85, v69
	v_add_f32_e32 v66, v185, v66
	v_exp_f32_e32 v86, v70
	v_add_f32_e32 v66, v82, v66
	v_exp_f32_e32 v87, v71
	v_add_f32_e32 v66, v83, v66
	v_exp_f32_e32 v88, v72
	v_add_f32_e32 v66, v84, v66
	v_exp_f32_e32 v89, v73
	v_add_f32_e32 v66, v85, v66
	v_exp_f32_e32 v90, v74
	v_add_f32_e32 v66, v86, v66
	v_exp_f32_e32 v91, v75
	v_add_f32_e32 v66, v87, v66
	v_exp_f32_e32 v92, v76
	v_add_f32_e32 v66, v88, v66
	v_exp_f32_e32 v93, v77
	v_add_f32_e32 v66, v89, v66
	v_exp_f32_e32 v94, v78
	v_add_f32_e32 v66, v90, v66
	v_exp_f32_e32 v95, v79
	v_add_f32_e32 v66, v91, v66
	v_exp_f32_e32 v96, v80
	v_add_f32_e32 v66, v92, v66
	v_exp_f32_e32 v97, v81
	v_add_f32_e32 v66, v93, v66
	v_add_f32_e32 v66, v94, v66
	v_add_f32_e32 v66, v95, v66
	v_add_f32_e32 v66, v96, v66
	s_lshl_b32 s0, s33, 2
	v_add_f32_e32 v66, v97, v66
	s_add_i32 s24, s0, 0
	v_mov_b32_e32 v67, v66
	s_add_i32 s24, s24, 0x1e000
	s_nop 0
	v_permlane32_swap_b32_e32 v66, v67
	v_cvt_pk_bf16_f32 v68, v139, v141
	v_cvt_pk_bf16_f32 v69, v143, v145
	v_cvt_pk_bf16_f32 v70, v147, v149
	v_cvt_pk_bf16_f32 v71, v176, v177
	v_cvt_pk_bf16_f32 v72, v178, v179
	v_cvt_pk_bf16_f32 v73, v180, v181
	v_cvt_pk_bf16_f32 v74, v182, v183
	v_cvt_pk_bf16_f32 v75, v184, v185
	v_cvt_pk_bf16_f32 v76, v82, v83
	v_cvt_pk_bf16_f32 v77, v84, v85
	v_cvt_pk_bf16_f32 v78, v86, v87
	v_cvt_pk_bf16_f32 v79, v88, v89
	v_cvt_pk_bf16_f32 v80, v90, v91
	v_cvt_pk_bf16_f32 v81, v92, v93
	v_cvt_pk_bf16_f32 v82, v94, v95
	v_cvt_pk_bf16_f32 v83, v96, v97
	ds_read_b64_tr_b16 v[84:85], v169 offset:0
	ds_read_b64_tr_b16 v[86:87], v169 offset:0x800
	ds_read_b64_tr_b16 v[88:89], v169 offset:0x1000
	ds_read_b64_tr_b16 v[90:91], v169 offset:0x1800
	ds_read_b64_tr_b16 v[92:93], v169 offset:0x2000
	ds_read_b64_tr_b16 v[94:95], v169 offset:0x2800
	ds_read_b64_tr_b16 v[96:97], v169 offset:0x3000
	ds_read_b64_tr_b16 v[98:99], v169 offset:0x3800
	s_waitcnt lgkmcnt(0)
	s_nop 0
	v_mfma_f32_32x32x16_bf16 v[2:17], v[68:71], v[84:87], v[2:17]
	ds_read_b64_tr_b16 v[84:85], v169 offset:0x200
	ds_read_b64_tr_b16 v[86:87], v169 offset:0xa00
	v_mfma_f32_32x32x16_bf16 v[2:17], v[72:75], v[88:91], v[2:17]
	ds_read_b64_tr_b16 v[88:89], v169 offset:0x1200
	ds_read_b64_tr_b16 v[90:91], v169 offset:0x1a00
	v_mfma_f32_32x32x16_bf16 v[2:17], v[76:79], v[92:95], v[2:17]
	ds_read_b64_tr_b16 v[92:93], v169 offset:0x2200
	ds_read_b64_tr_b16 v[94:95], v169 offset:0x2a00
	ds_read_b64_tr_b16 v[100:101], v169 offset:0x3200
	ds_read_b64_tr_b16 v[102:103], v169 offset:0x3a00
	s_waitcnt lgkmcnt(0)
	v_mfma_f32_32x32x16_bf16 v[2:17], v[80:83], v[96:99], v[2:17]
	v_mfma_f32_32x32x16_bf16 v[18:33], v[68:71], v[84:87], v[18:33]
	ds_read_b64_tr_b16 v[84:85], v169 offset:0x400
	ds_read_b64_tr_b16 v[86:87], v169 offset:0xc00
	v_mfma_f32_32x32x16_bf16 v[18:33], v[72:75], v[88:91], v[18:33]
	ds_read_b64_tr_b16 v[88:89], v169 offset:0x1400
	ds_read_b64_tr_b16 v[90:91], v169 offset:0x1c00
	v_mfma_f32_32x32x16_bf16 v[18:33], v[76:79], v[92:95], v[18:33]
	ds_read_b64_tr_b16 v[92:93], v169 offset:0x2400
	ds_read_b64_tr_b16 v[94:95], v169 offset:0x2c00
	ds_read_b64_tr_b16 v[96:97], v169 offset:0x3400
	ds_read_b64_tr_b16 v[98:99], v169 offset:0x3c00
	s_waitcnt lgkmcnt(0)
	v_mfma_f32_32x32x16_bf16 v[18:33], v[80:83], v[100:103], v[18:33]
	v_mfma_f32_32x32x16_bf16 v[34:49], v[68:71], v[84:87], v[34:49]
	ds_read_b64_tr_b16 v[84:85], v169 offset:0x600
	ds_read_b64_tr_b16 v[86:87], v169 offset:0xe00
	v_mfma_f32_32x32x16_bf16 v[34:49], v[72:75], v[88:91], v[34:49]
	ds_read_b64_tr_b16 v[88:89], v169 offset:0x1600
	ds_read_b64_tr_b16 v[90:91], v169 offset:0x1e00
	v_mfma_f32_32x32x16_bf16 v[34:49], v[76:79], v[92:95], v[34:49]
	ds_read_b64_tr_b16 v[92:93], v169 offset:0x2600
	ds_read_b64_tr_b16 v[94:95], v169 offset:0x2e00
	ds_read_b64_tr_b16 v[100:101], v169 offset:0x3600
	ds_read_b64_tr_b16 v[102:103], v169 offset:0x3e00
	s_waitcnt lgkmcnt(0)
	v_mfma_f32_32x32x16_bf16 v[34:49], v[80:83], v[96:99], v[34:49]
	v_mfma_f32_32x32x16_bf16 v[50:65], v[68:71], v[84:87], v[50:65]
	s_barrier
	v_mfma_f32_32x32x16_bf16 v[50:65], v[72:75], v[88:91], v[50:65]
	v_mfma_f32_32x32x16_bf16 v[50:65], v[76:79], v[92:95], v[50:65]
	v_mfma_f32_32x32x16_bf16 v[50:65], v[80:83], v[100:103], v[50:65]
	v_mov_b32_e32 v253, v219
	s_nop 1
	v_permlane32_swap_b32_e32 v219, v253
	v_add_f32_e32 v219, v219, v253
	s_and_saveexec_b64 s[0:1], s[2:3]
	s_cbranch_execz .LBB0_2317
	v_add_f32_e32 v66, v66, v67
	v_add_f32_e32 v66, v135, v66
	v_add_f32_e32 v66, v66, v219
	v_lshl_add_u32 v67, v165, 2, s24
	ds_write_b32 v67, v66
	s_branch .LBB0_2317
